# SSD and mLSTM conv+silu blocks rewritten: each lane handles a channel pair for four tokens with packed f32 math, b32 LDS reads and writes; GLA gate dot with natural-order packed pairs
# speedup vs baseline: 1.0178x; 1.0178x over previous
.LBB0_404:
	s_or_b64 exec, exec, s[56:57]
	s_and_b64 s[30:31], s[40:41], exec
	s_mov_b32 s9, 0xab34000
	s_cselect_b32 s9, s9, 0xed34000
	v_readlane_b32 s30, v254, 53
	s_add_u32 s29, s30, s9
	v_min_i32_e32 v0, 0xbf, v69
	s_movk_i32 s9, 0xffbf
	v_add_u32_e32 v0, 64, v0
	v_cmp_lt_i32_e32 vcc, s9, v69
	v_min_i32_e32 v4, 0xbf, v70
	v_add_u32_e32 v4, 64, v4
	v_cndmask_b32_e32 v0, 0, v0, vcc
	v_cmp_lt_i32_e32 vcc, s9, v70
	v_cndmask_b32_e64 v78, 64, -1, s[44:45]
	v_sub_u32_e32 v1, 0xff, v0
	v_cndmask_b32_e32 v4, 0, v4, vcc
	v_sub_u32_e32 v5, 0xff, v4
	v_add_u32_e32 v8, 64, v78
	v_sub_u32_e32 v9, 0xbf, v78
	v_add_u32_e32 v14, 64, v71
	v_sub_u32_e32 v15, 0xbf, v71
	v_cndmask_b32_e64 v0, v1, v0, s[40:41]
	v_cndmask_b32_e64 v4, v5, v4, s[40:41]
	v_cndmask_b32_e64 v8, v9, v8, s[40:41]
	v_cndmask_b32_e64 v14, v15, v14, s[40:41]
	v_or_b32_e32 v20, 64, v62
	v_xor_b32_e32 v21, 0xbf, v62
	v_add_u32_e32 v0, s16, v0
	v_mov_b64_e32 v[12:13], s[12:13]
	v_add_u32_e32 v4, s16, v4
	v_add_u32_e32 v8, s16, v8
	v_add_u32_e32 v14, s16, v14
	v_cndmask_b32_e64 v20, v21, v20, s[40:41]
	v_mad_i64_i32 v[0:1], s[34:35], v0, s20, v[12:13]
	v_mad_i64_i32 v[4:5], s[34:35], v4, s20, v[12:13]
	v_mul_lo_u32 v8, v8, s20
	v_mov_b32_e32 v9, v169
	v_mad_i64_i32 v[12:13], s[34:35], v14, s20, v[12:13]
	v_or_b32_e32 v20, s16, v20
	v_mov_b32_e32 v19, v169
	v_lshl_add_u64 v[8:9], s[12:13], 0, v[8:9]
	v_lshl_add_u64 v[12:13], v[12:13], 0, s[84:85]
	v_mul_lo_u32 v20, v20, s21
	v_mov_b32_e32 v21, v169
	v_lshl_add_u64 v[0:1], v[0:1], 0, v[18:19]
	v_lshl_add_u64 v[4:5], v[4:5], 0, v[18:19]
	v_lshl_add_u64 v[8:9], v[8:9], 0, v[18:19]
	v_lshl_add_u64 v[12:13], v[12:13], 0, v[168:169]
	v_lshl_add_u64 v[20:21], s[14:15], 0, v[20:21]
	s_mov_b32 s9, s85
	v_lshl_add_u64 v[0:1], v[0:1], 0, s[84:85]
	v_lshl_add_u64 v[4:5], v[4:5], 0, s[84:85]
	v_lshl_add_u64 v[8:9], v[8:9], 0, s[84:85]
	v_add_co_u32_e32 v12, vcc, s38, v12
	v_lshl_add_u64 v[20:21], v[20:21], 0, s[8:9]
	s_mov_b32 s77, s85
	v_ashrrev_i32_e32 v31, 6, v16
	v_lshl_add_u64 v[0:1], v[0:1], 0, v[168:169]
	v_lshl_add_u64 v[4:5], v[4:5], 0, v[168:169]
	v_lshl_add_u64 v[8:9], v[8:9], 0, v[168:169]
	v_addc_co_u32_e32 v13, vcc, 0, v13, vcc
	v_lshl_add_u64 v[20:21], v[20:21], 0, s[76:77]
	s_movk_i32 s9, 0x880
	v_lshlrev_b32_e32 v80, 1, v62
	global_load_dwordx4 v[0:3], v[0:1], off offset:3664
	v_mul_lo_u32 v79, v31, s9
	global_load_dwordx4 v[4:7], v[4:5], off offset:3664
	s_movk_i32 s9, 0x480
	global_load_dwordx4 v[8:11], v[8:9], off offset:3664
	s_movk_i32 s34, 0x90
	global_load_dwordx4 v[12:15], v[12:13], off offset:592
	s_nop 0
	global_load_dword v82, v[20:21], off offset:256
	global_load_dword v83, v[20:21], off offset:272
	v_add_u32_e32 v20, 0, v80
	v_add_u32_e32 v22, v20, v79
	s_waitcnt lgkmcnt(0)
	s_barrier
	ds_read_u16 v21, v22 offset:59904
	ds_read_u16 v23, v22 offset:60176
	ds_read_u16 v24, v22 offset:60448
	v_mov_b32_e32 v51, v50
	v_mov_b32_e32 v49, v48
	s_waitcnt lgkmcnt(2)
	v_lshlrev_b32_e32 v21, 16, v21
	s_waitcnt lgkmcnt(1)
	v_lshlrev_b32_e32 v23, 16, v23
	v_mul_f32_e32 v25, v64, v23
	s_waitcnt lgkmcnt(0)
	v_lshlrev_b32_e32 v24, 16, v24
	v_fmac_f32_e32 v25, v63, v21
	v_fmac_f32_e32 v25, v65, v24
	v_add_f32_e32 v21, v66, v25
	v_mul_f32_e32 v25, 0xbfb8aa3b, v21
	v_exp_f32_e32 v25, v25
	v_mul_f32_e32 v26, v64, v24
	v_fmac_f32_e32 v26, v63, v23
	v_mov_b32_e32 v53, v52
	v_add_f32_e32 v25, 1.0, v25
	v_rcp_f32_e32 v25, v25
	v_mov_b32_e32 v55, v54
	v_readlane_b32 s31, v254, 54
	s_addc_u32 s30, s31, 0
	v_mul_f32_e32 v21, v21, v25
	v_mul_lo_u32 v25, v31, s9
	v_cvt_pk_bf16_f32 v21, v21, s0
	v_add_u32_e32 v81, v20, v25
	ds_write_b16 v81, v21
	v_lshl_or_b32 v21, v31, 3, 1
	v_mul_lo_u32 v84, v21, s36
	v_add_u32_e32 v32, v20, v84
	ds_read_u16 v25, v32 offset:60448
	v_mul_lo_u32 v21, v21, s34
	v_add_u32_e32 v85, v20, v21
	ds_read_u16 v20, v32 offset:60720
	s_add_i32 s9, 0, 0x13720
	s_waitcnt lgkmcnt(1)
	v_lshlrev_b32_e32 v25, 16, v25
	v_fmac_f32_e32 v26, v65, v25
	v_add_f32_e32 v23, v66, v26
	v_mul_f32_e32 v26, 0xbfb8aa3b, v23
	v_exp_f32_e32 v26, v26
	v_mul_f32_e32 v21, v64, v25
	s_waitcnt lgkmcnt(0)
	v_lshlrev_b32_e32 v20, 16, v20
	v_fmac_f32_e32 v21, v63, v24
	v_add_f32_e32 v26, 1.0, v26
	v_rcp_f32_e32 v26, v26
	v_fmac_f32_e32 v21, v65, v20
	v_add_f32_e32 v21, v66, v21
	v_lshl_add_u32 v92, v31, 5, s9
	v_mul_f32_e32 v23, v23, v26
	v_cvt_pk_bf16_f32 v23, v23, s0
	ds_write_b16 v85, v23
	v_mul_f32_e32 v23, 0xbfb8aa3b, v21
	v_exp_f32_e32 v23, v23
	s_add_i32 s31, 0, 0x13020
	v_and_b32_e32 v28, 1, v31
	v_lshrrev_b32_e32 v30, 4, v62
	v_add_f32_e32 v23, 1.0, v23
	v_rcp_f32_e32 v23, v23
	v_lshlrev_b32_e32 v29, 5, v28
	v_and_b32_e32 v95, 48, v16
	v_cmp_gt_u32_e32 vcc, 16, v16
	v_mul_f32_e32 v21, v21, v23
	v_cvt_pk_bf16_f32 v21, v21, s0
	ds_write_b16 v85, v21 offset:144
	ds_read_u16 v21, v32 offset:60992
	v_mul_f32_e32 v23, v64, v20
	v_fmac_f32_e32 v23, v63, v25
	v_mov_b32_e32 v16, 0x4510
	s_lshl_b32 s28, s28, 13
	s_waitcnt lgkmcnt(0)
	v_lshlrev_b32_e32 v21, 16, v21
	v_fmac_f32_e32 v23, v65, v21
	v_add_f32_e32 v23, v66, v23
	v_mul_f32_e32 v24, 0xbfb8aa3b, v23
	v_exp_f32_e32 v24, v24
	v_cndmask_b32_e64 v106, v16, 0, vcc
	v_lshlrev_b32_e32 v16, 3, v30
	v_mul_u32_u24_e32 v103, 0x90, v17
	v_add_f32_e32 v24, 1.0, v24
	v_rcp_f32_e32 v24, v24
	v_mad_u32_u24 v104, v17, s34, 0
	v_cmp_eq_u32_e64 s[50:51], 0, v17
	v_cmp_lt_u32_e64 s[52:53], 1, v17
	v_mul_f32_e32 v23, v23, v24
	v_cvt_pk_bf16_f32 v23, v23, s0
	ds_write_b16 v85, v23 offset:288
	ds_read_u16 v23, v32 offset:61264
	v_mul_f32_e32 v24, v64, v21
	v_fmac_f32_e32 v24, v63, v20
	v_cmp_lt_u32_e64 s[54:55], 3, v17
	v_cmp_lt_u32_e64 s[56:57], 7, v17
	s_waitcnt lgkmcnt(0)
	v_lshlrev_b32_e32 v23, 16, v23
	v_fmac_f32_e32 v24, v65, v23
	v_add_f32_e32 v20, v66, v24
	v_mul_f32_e32 v24, 0xbfb8aa3b, v20
	v_exp_f32_e32 v24, v24
	v_lshl_add_u64 v[18:19], s[12:13], 0, v[18:19]
	v_lshl_add_u64 v[18:19], v[18:19], 0, s[84:85]
	v_lshl_add_u64 v[56:57], v[18:19], 0, v[168:169]
	v_add_f32_e32 v24, 1.0, v24
	v_rcp_f32_e32 v24, v24
	v_lshlrev_b32_e32 v18, 6, v28
	v_mov_b32_e32 v19, v169
	s_mov_b32 s17, 0
	v_mul_f32_e32 v20, v20, v24
	v_cvt_pk_bf16_f32 v20, v20, s0
	ds_write_b16 v85, v20 offset:432
	ds_read_u16 v20, v32 offset:61536
	v_mul_f32_e32 v24, v64, v23
	v_fmac_f32_e32 v24, v63, v21
	v_cmp_eq_u32_e64 s[48:49], 0, v28
	v_add_u32_e32 v86, 0x110, v84
	s_waitcnt lgkmcnt(0)
	v_lshlrev_b32_e32 v20, 16, v20
	v_fmac_f32_e32 v24, v65, v20
	v_add_f32_e32 v21, v66, v24
	v_mul_f32_e32 v24, 0xbfb8aa3b, v21
	v_exp_f32_e32 v24, v24
	v_add_u32_e32 v87, 0x220, v84
	v_add_u32_e32 v88, 0x330, v84
	v_add_u32_e32 v89, 0x440, v84
	v_add_f32_e32 v24, 1.0, v24
	v_rcp_f32_e32 v24, v24
	v_add_u32_e32 v90, 0x550, v84
	v_add_u32_e32 v91, 0x660, v84
	v_add_u32_e32 v97, 0, v95
	v_mul_f32_e32 v21, v21, v24
	v_cvt_pk_bf16_f32 v21, v21, s0
	ds_write_b16 v85, v21 offset:576
	ds_read_u16 v21, v32 offset:61808
	v_mul_f32_e32 v24, v64, v20
	v_fmac_f32_e32 v24, v63, v23
	v_cndmask_b32_e64 v105, 64, -1, vcc
	v_cmp_lt_u32_e64 s[58:59], 31, v62
	s_waitcnt lgkmcnt(0)
	v_lshlrev_b32_e32 v21, 16, v21
	v_fmac_f32_e32 v24, v65, v21
	v_add_f32_e32 v23, v66, v24
	v_mul_f32_e32 v24, 0xbfb8aa3b, v23
	v_exp_f32_e32 v24, v24
	v_mul_f32_e32 v21, v64, v21
	v_fmac_f32_e32 v21, v63, v20
	v_mov_b32_e32 v115, 0
	v_add_f32_e32 v24, 1.0, v24
	v_rcp_f32_e32 v24, v24
	s_nop 0
	v_mul_f32_e32 v23, v23, v24
	v_cvt_pk_bf16_f32 v23, v23, s0
	ds_write_b16 v85, v23 offset:720
	ds_read_u16 v23, v32 offset:62080
	s_waitcnt lgkmcnt(0)
	v_lshlrev_b32_e32 v23, 16, v23
	v_fmac_f32_e32 v21, v65, v23
	v_add_f32_e32 v20, v66, v21
	v_mul_f32_e32 v21, 0xbfb8aa3b, v20
	v_exp_f32_e32 v21, v21
	s_nop 0
	v_add_f32_e32 v21, 1.0, v21
	v_rcp_f32_e32 v21, v21
	s_nop 0
	v_mul_f32_e32 v20, v20, v21
	v_cvt_pk_bf16_f32 v20, v20, s0
	ds_write_b16 v85, v20 offset:864
	ds_read_u16 v20, v32 offset:61392
	ds_read_u16 v21, v32 offset:61664
	ds_read_u16 v23, v32 offset:61936
	ds_read_u16 v24, v32 offset:62208
	ds_read_u16 v26, v32 offset:60848
	ds_read_u16 v27, v32 offset:61120
	ds_read_u16 v33, v22 offset:60576
	ds_read_u16 v32, v32 offset:60576
	s_waitcnt lgkmcnt(7)
	v_lshlrev_b32_e32 v20, 16, v20
	s_waitcnt lgkmcnt(6)
	v_lshlrev_b32_e32 v21, 16, v21
	s_waitcnt lgkmcnt(3)
	v_lshlrev_b32_e32 v26, 16, v26
	s_waitcnt lgkmcnt(1)
	v_lshlrev_b32_e32 v36, 16, v33
	s_waitcnt lgkmcnt(0)
	v_lshlrev_b32_e32 v37, 16, v32
	ds_read_u16 v32, v22 offset:60032
	ds_read_u16 v22, v22 offset:60304
	v_lshlrev_b32_e32 v27, 16, v27
	v_lshlrev_b32_e32 v25, 16, v23
	v_lshlrev_b32_e32 v23, 16, v24
	s_waitcnt lgkmcnt(1)
	v_lshlrev_b32_e32 v38, 16, v32
	s_waitcnt lgkmcnt(0)
	v_lshlrev_b32_e32 v39, 16, v22
	v_pk_mov_b32 v[40:41], v[38:39], v[36:37] op_sel:[1,0]
	ds_read_b128 v[32:35], v92
	v_pk_mul_f32 v[40:41], v[50:51], v[40:41] op_sel_hi:[0,1]
	v_pk_fma_f32 v[38:39], v[48:49], v[38:39], v[40:41] op_sel_hi:[0,1,1]
	v_pk_fma_f32 v[38:39], v[52:53], v[36:37], v[38:39] op_sel_hi:[0,1,1]
	v_pk_add_f32 v[38:39], v[54:55], v[38:39] op_sel_hi:[0,1]
	v_mul_f32_e32 v22, 0xbfb8aa3b, v38
	v_exp_f32_e32 v22, v22
	v_mov_b32_e32 v24, v21
	v_add_f32_e32 v22, 1.0, v22
	v_rcp_f32_e32 v40, v22
	v_mul_f32_e32 v22, 0xbfb8aa3b, v39
	v_exp_f32_e32 v22, v22
	s_nop 0
	v_add_f32_e32 v22, 1.0, v22
	v_rcp_f32_e32 v41, v22
	s_nop 0
	v_pk_mul_f32 v[38:39], v[38:39], v[40:41]
	s_nop 0
	v_pk_mul_f32 v[38:39], v[38:39], s[92:93] op_sel_hi:[1,0]
	v_pk_mov_b32 v[40:41], v[26:27], v[20:21] op_sel:[1,0]
	v_cvt_pk_bf16_f32 v22, v38, s0
	ds_write_b16 v81, v22 offset:9216
	v_cvt_pk_bf16_f32 v22, v39, s0
	s_waitcnt lgkmcnt(1)
	v_pk_mul_f32 v[38:39], v[32:33], v[38:39]
	v_pk_mov_b32 v[32:33], v[36:37], v[26:27] op_sel:[1,0]
	ds_write_b16 v85, v22 offset:9216
	v_pk_mul_f32 v[32:33], v[50:51], v[32:33] op_sel_hi:[0,1]
	v_pk_fma_f32 v[32:33], v[48:49], v[36:37], v[32:33] op_sel_hi:[0,1,1]
	v_pk_fma_f32 v[32:33], v[52:53], v[26:27], v[32:33] op_sel_hi:[0,1,1]
	v_pk_add_f32 v[32:33], v[54:55], v[32:33] op_sel_hi:[0,1]
	v_mul_f32_e32 v22, 0xbfb8aa3b, v32
	v_exp_f32_e32 v22, v22
	v_pk_mul_f32 v[40:41], v[50:51], v[40:41] op_sel_hi:[0,1]
	v_pk_fma_f32 v[26:27], v[48:49], v[26:27], v[40:41] op_sel_hi:[0,1,1]
	v_pk_fma_f32 v[26:27], v[52:53], v[20:21], v[26:27] op_sel_hi:[0,1,1]
	v_add_f32_e32 v22, 1.0, v22
	v_rcp_f32_e32 v36, v22
	v_mul_f32_e32 v22, 0xbfb8aa3b, v33
	v_exp_f32_e32 v22, v22
	v_pk_add_f32 v[26:27], v[54:55], v[26:27] op_sel_hi:[0,1]
	v_add_f32_e32 v22, 1.0, v22
	v_rcp_f32_e32 v37, v22
	s_nop 0
	v_pk_mul_f32 v[32:33], v[32:33], v[36:37]
	s_nop 0
	v_pk_mul_f32 v[32:33], v[32:33], s[92:93] op_sel_hi:[1,0]
	s_nop 0
	v_cvt_pk_bf16_f32 v22, v32, s0
	ds_write_b16 v85, v22 offset:9360
	v_cvt_pk_bf16_f32 v22, v33, s0
	ds_write_b16 v85, v22 offset:9504
	v_mul_f32_e32 v22, 0xbfb8aa3b, v26
	v_exp_f32_e32 v22, v22
	v_pk_mul_f32 v[36:37], v[34:35], v[32:33]
	ds_read_b128 v[32:35], v92 offset:16
	v_add_f32_e32 v22, 1.0, v22
	v_rcp_f32_e32 v40, v22
	v_mul_f32_e32 v22, 0xbfb8aa3b, v27
	v_exp_f32_e32 v22, v22
	s_nop 0
	v_add_f32_e32 v22, 1.0, v22
	v_rcp_f32_e32 v41, v22
	s_nop 0
	v_pk_mul_f32 v[26:27], v[26:27], v[40:41]
	s_nop 0
	v_pk_mul_f32 v[26:27], v[26:27], s[92:93] op_sel_hi:[1,0]
	s_nop 0
	v_cvt_pk_bf16_f32 v22, v26, s0
	ds_write_b16 v85, v22 offset:9648
	v_cvt_pk_bf16_f32 v22, v27, s0
	ds_write_b16 v85, v22 offset:9792
	v_mov_b32_e32 v22, v25
	v_pk_mul_f32 v[24:25], v[50:51], v[24:25] op_sel_hi:[0,1]
	v_pk_fma_f32 v[20:21], v[48:49], v[20:21], v[24:25] op_sel_hi:[0,1,1]
	v_pk_fma_f32 v[20:21], v[52:53], v[22:23], v[20:21] op_sel_hi:[0,1,1]
	v_pk_add_f32 v[20:21], v[54:55], v[20:21] op_sel_hi:[0,1]
	v_mul_f32_e32 v22, 0xbfb8aa3b, v20
	v_mul_f32_e32 v23, 0xbfb8aa3b, v21
	v_exp_f32_e32 v22, v22
	v_exp_f32_e32 v23, v23
	s_waitcnt lgkmcnt(2)
	v_pk_mul_f32 v[26:27], v[32:33], v[26:27]
	v_lshlrev_b32_e32 v32, 8, v30
	v_add_f32_e32 v22, 1.0, v22
	v_add_f32_e32 v23, 1.0, v23
	v_rcp_f32_e32 v22, v22
	v_rcp_f32_e32 v23, v23
	v_add_u32_e32 v33, v104, v16
	v_pk_mul_f32 v[20:21], v[20:21], v[22:23]
	s_nop 0
	v_pk_mul_f32 v[20:21], v[20:21], s[92:93] op_sel_hi:[1,0]
	s_nop 0
	v_cvt_pk_bf16_f32 v22, v20, s0
	v_pk_mul_f32 v[24:25], v[34:35], v[20:21]
	ds_write_b16 v85, v22 offset:9936
	v_cvt_pk_bf16_f32 v22, v21, s0
	v_cvt_pk_bf16_f32 v23, v24, v25
	v_mul_u32_u24_e32 v24, 0x90, v62
	v_lshlrev_b32_e32 v25, 4, v31
	ds_write_b16 v85, v22 offset:10080
	v_cvt_pk_bf16_f32 v20, v38, v39
	v_cvt_pk_bf16_f32 v21, v36, v37
	v_cvt_pk_bf16_f32 v22, v26, v27
	v_add3_u32 v93, 0, v24, v25
	ds_write_b128 v93, v[20:23] offset:18432
	v_and_b32_e32 v20, -16, v71
	v_or_b32_e32 v94, v20, v17
	v_lshlrev_b32_e32 v22, 2, v62
	v_mul_lo_u32 v21, v94, s34
	v_add_u32_e32 v98, s31, v22
	s_add_i32 s31, 0, 0x13120
	v_add_u32_e32 v31, 0, v21
	v_lshlrev_b32_e32 v21, 2, v30
	v_add_u32_e32 v99, s31, v22
	s_add_i32 s31, 0, 0x13220
	v_add_u32_e32 v101, s9, v22
	v_readlane_b32 s9, v253, 45
	v_lshlrev_b32_e32 v30, 1, v20
	v_or_b32_e32 v20, v29, v17
	v_or_b32_e32 v109, v29, v21
	s_add_u32 s8, s14, s8
	v_lshl_add_u32 v102, v94, 2, s9
	v_mul_u32_u24_e32 v108, 0x90, v20
	v_or_b32_e32 v20, 3, v109
	s_addc_u32 s9, s15, 0
	v_cmp_gt_i32_e64 s[64:65], v20, v94
	v_or_b32_e32 v20, 16, v29
	s_add_u32 s8, s8, s76
	v_or_b32_e32 v17, v20, v17
	s_addc_u32 s9, s9, 0
	v_mul_u32_u24_e32 v110, 0x90, v17
	v_or_b32_e32 v17, v20, v21
	s_add_u32 s34, s29, s84
	v_cmp_gt_i32_e64 s[68:69], v17, v94
	v_cmp_lt_i32_e64 s[70:71], v17, v94
	v_or_b32_e32 v20, 3, v17
	v_or_b32_e32 v21, 2, v17
	v_lshlrev_b32_e32 v29, 1, v17
	s_addc_u32 s35, s30, 0
	v_mov_b32_e32 v17, v169
	v_add_u32_e32 v100, s31, v22
	v_add3_u32 v107, 0, v16, v30
	v_or_b32_e32 v22, 2, v109
	v_lshlrev_b32_e32 v34, 1, v109
	v_lshl_add_u64 v[16:17], s[34:35], 0, v[16:17]
	v_add_u32_e32 v96, v31, v95
	v_cmp_gt_i32_e64 s[60:61], v109, v94
	v_cmp_lt_i32_e64 s[62:63], v109, v94
	v_cmp_gt_i32_e64 s[66:67], v22, v94
	v_cmp_gt_i32_e64 s[72:73], v20, v94
	v_cmp_gt_i32_e64 s[74:75], v21, v94
	v_lshl_add_u64 v[58:59], v[16:17], 0, v[18:19]
	v_mov_b32_e32 v24, 0
	v_mov_b32_e32 v25, 0
	v_mov_b32_e32 v26, 0
	v_mov_b32_e32 v27, 0
	v_mov_b32_e32 v16, 0
	v_mov_b32_e32 v17, 0
	v_mov_b32_e32 v18, 0
	v_mov_b32_e32 v19, 0
	v_mov_b32_e32 v20, 0
	v_mov_b32_e32 v21, 0
	v_mov_b32_e32 v22, 0
	v_mov_b32_e32 v23, 0
	v_add_u32_e32 v111, v31, v34
	v_add_u32_e32 v112, v31, v29
	v_add_u32_e32 v113, v102, v32
	v_add_u32_e32 v114, v33, v30
	s_mov_b32 s29, 0
	s_waitcnt lgkmcnt(0)
	s_barrier
	v_lshrrev_b32_e32 v196, 5, v171
	v_and_b32_e32 v197, 31, v171
	v_lshlrev_b32_e32 v196, 2, v196
	v_mul_u32_u24_e32 v198, 0x110, v196
	v_lshl_add_u32 v198, v197, 2, v198
	v_add_u32_e32 v198, 0xea00, v198
	v_mul_u32_u24_e32 v199, 0x90, v196
	v_lshl_add_u32 v199, v197, 2, v199
	v_mul_u32_u24_e32 v200, 0x120, v197
	v_lshl_add_u32 v200, v196, 1, v200
	v_lshlrev_b32_e32 v201, 2, v196
	v_add_u32_e32 v201, 0x13720, v201
	v_lshlrev_b32_e32 v202, 3, v197
	v_add_u32_e32 v203, 4, v202
	ds_bpermute_b32 v172, v202, v63
	ds_bpermute_b32 v173, v203, v63
	ds_bpermute_b32 v174, v202, v64
	ds_bpermute_b32 v175, v203, v64
	ds_bpermute_b32 v176, v202, v65
	ds_bpermute_b32 v177, v203, v65
	ds_bpermute_b32 v178, v202, v66
	ds_bpermute_b32 v179, v203, v66
	ds_bpermute_b32 v180, v202, v48
	ds_bpermute_b32 v181, v203, v48
	ds_bpermute_b32 v182, v202, v50
	ds_bpermute_b32 v183, v203, v50
	ds_bpermute_b32 v184, v202, v52
	ds_bpermute_b32 v185, v203, v52
	ds_bpermute_b32 v186, v202, v54
	ds_bpermute_b32 v187, v203, v54
	s_waitcnt lgkmcnt(0)
	s_branch .LBB0_406
.LBB0_405:
	s_or_b64 exec, exec, s[76:77]
	v_mov_b32_e32 v31, s31
	ds_read_b32 v31, v31 offset:252
	s_add_i32 s17, s17, 64
	s_mul_i32 s35, s78, 0x7b80
	s_mul_i32 s29, s78, 0x7c00
	s_mul_i32 s78, s78, 0x16c20
	v_add_u32_e32 v122, s35, v198
	v_add_u32_e32 v124, s29, v201
	v_add_u32_e32 v123, s78, v200
	v_mov_b32_e32 v154, 0xbfb8aa3b
	ds_read_b32 v131, v122 offset:128
	ds_read_b32 v133, v122 offset:400
	ds_read_b32 v135, v122 offset:672
	ds_read_b32 v137, v122 offset:944
	ds_read_b32 v139, v122 offset:1216
	ds_read_b32 v141, v122 offset:1488
	ds_read_b128 v[156:159], v124
	s_waitcnt lgkmcnt(5)
	v_add_f32_e32 v115, v30, v31
	v_lshlrev_b32_e32 v130, 16, v131
	v_and_b32_e32 v131, 0xffff0000, v131
	v_lshlrev_b32_e32 v132, 16, v133
	v_and_b32_e32 v133, 0xffff0000, v133
	s_waitcnt lgkmcnt(2)
	v_lshlrev_b32_e32 v134, 16, v135
	v_and_b32_e32 v135, 0xffff0000, v135
	v_lshlrev_b32_e32 v136, 16, v137
	v_and_b32_e32 v137, 0xffff0000, v137
	v_lshlrev_b32_e32 v138, 16, v139
	v_and_b32_e32 v139, 0xffff0000, v139
	s_waitcnt lgkmcnt(1)
	v_lshlrev_b32_e32 v140, 16, v141
	v_and_b32_e32 v141, 0xffff0000, v141
	v_pk_mul_f32 v[160:161], v[180:181], v[130:131]
	v_pk_mul_f32 v[162:163], v[180:181], v[132:133]
	v_pk_mul_f32 v[164:165], v[180:181], v[134:135]
	v_pk_mul_f32 v[166:167], v[180:181], v[136:137]
	v_pk_fma_f32 v[160:161], v[182:183], v[132:133], v[160:161]
	v_pk_fma_f32 v[162:163], v[182:183], v[134:135], v[162:163]
	v_pk_fma_f32 v[164:165], v[182:183], v[136:137], v[164:165]
	v_pk_fma_f32 v[166:167], v[182:183], v[138:139], v[166:167]
	v_pk_fma_f32 v[160:161], v[184:185], v[134:135], v[160:161]
	v_pk_fma_f32 v[162:163], v[184:185], v[136:137], v[162:163]
	v_pk_fma_f32 v[164:165], v[184:185], v[138:139], v[164:165]
	v_pk_fma_f32 v[166:167], v[184:185], v[140:141], v[166:167]
	v_pk_add_f32 v[160:161], v[186:187], v[160:161]
	v_pk_add_f32 v[162:163], v[186:187], v[162:163]
	v_pk_add_f32 v[164:165], v[186:187], v[164:165]
	v_pk_add_f32 v[166:167], v[186:187], v[166:167]
	v_pk_mul_f32 v[188:189], v[160:161], v[154:155] op_sel_hi:[1,0]
	v_pk_mul_f32 v[190:191], v[162:163], v[154:155] op_sel_hi:[1,0]
	v_pk_mul_f32 v[192:193], v[164:165], v[154:155] op_sel_hi:[1,0]
	v_pk_mul_f32 v[194:195], v[166:167], v[154:155] op_sel_hi:[1,0]
	v_exp_f32_e32 v188, v188
	v_exp_f32_e32 v190, v190
	v_exp_f32_e32 v192, v192
	v_exp_f32_e32 v194, v194
	v_exp_f32_e32 v189, v189
	v_exp_f32_e32 v191, v191
	v_exp_f32_e32 v193, v193
	v_exp_f32_e32 v195, v195
	v_pk_add_f32 v[188:189], v[188:189], 1.0 op_sel_hi:[1,0]
	v_pk_add_f32 v[190:191], v[190:191], 1.0 op_sel_hi:[1,0]
	v_pk_add_f32 v[192:193], v[192:193], 1.0 op_sel_hi:[1,0]
	v_pk_add_f32 v[194:195], v[194:195], 1.0 op_sel_hi:[1,0]
	v_rcp_f32_e32 v188, v188
	v_rcp_f32_e32 v190, v190
	v_rcp_f32_e32 v192, v192
	v_rcp_f32_e32 v194, v194
	v_rcp_f32_e32 v189, v189
	v_rcp_f32_e32 v191, v191
	v_rcp_f32_e32 v193, v193
	v_rcp_f32_e32 v195, v195
	v_pk_mul_f32 v[160:161], v[160:161], v[188:189]
	v_pk_mul_f32 v[162:163], v[162:163], v[190:191]
	v_pk_mul_f32 v[164:165], v[164:165], v[192:193]
	v_pk_mul_f32 v[166:167], v[166:167], v[194:195]
	v_pk_mul_f32 v[160:161], v[160:161], s[92:93] op_sel_hi:[1,0]
	v_pk_mul_f32 v[162:163], v[162:163], s[92:93] op_sel_hi:[1,0]
	v_pk_mul_f32 v[164:165], v[164:165], s[92:93] op_sel_hi:[1,0]
	v_pk_mul_f32 v[166:167], v[166:167], s[92:93] op_sel_hi:[1,0]
	v_cvt_pk_bf16_f32 v188, v160, v161
	v_cvt_pk_bf16_f32 v190, v162, v163
	v_cvt_pk_bf16_f32 v192, v164, v165
	v_cvt_pk_bf16_f32 v194, v166, v167
	ds_write_b32 v199, v188 offset:9216
	ds_write_b32 v199, v190 offset:9360
	ds_write_b32 v199, v192 offset:9504
	ds_write_b32 v199, v194 offset:9648
	s_waitcnt lgkmcnt(4)
	v_pk_mul_f32 v[196:197], v[160:161], v[156:157] op_sel_hi:[1,0]
	v_pk_mul_f32 v[202:203], v[162:163], v[156:157] op_sel:[0,1]
	v_pk_mul_f32 v[204:205], v[164:165], v[158:159] op_sel_hi:[1,0]
	v_pk_mul_f32 v[206:207], v[166:167], v[158:159] op_sel:[0,1]
	v_cvt_pk_bf16_f32 v188, v196, v202
	v_cvt_pk_bf16_f32 v189, v204, v206
	v_cvt_pk_bf16_f32 v190, v197, v203
	v_cvt_pk_bf16_f32 v191, v205, v207
	ds_write_b64 v123, v[188:189] offset:18432
	ds_write_b64 v123, v[190:191] offset:18576
	s_cmpk_eq_i32 s34, 0x84
	s_mov_b32 s29, s34
	s_waitcnt lgkmcnt(0)
	s_barrier
	s_cbranch_scc1 .LBB0_420
.LBB0_406:
	s_and_b32 s35, s29, 1
	s_mul_i32 s30, s35, 0x1f00
	s_lshl_b32 s30, s30, 2
	s_add_i32 s31, s30, 0
	s_add_i32 s30, s31, 0x13220
	s_add_i32 s34, s31, 0x13120
	v_add_u32_e32 v125, v97, v108
	ds_read_b128 v[128:131], v125 offset:9216
	ds_read_b128 v[132:135], v125 offset:9280
	v_lshl_add_u32 v126, v109, 2, s34
	ds_read_b128 v[136:139], v126
	ds_read_b128 v[140:143], v125 offset:48384
	ds_read_b128 v[144:147], v125 offset:48448
	v_add_u32_e32 v127, v97, v110
	ds_read_b128 v[148:151], v127 offset:9280
	ds_read_b128 v[152:155], v127 offset:9216
	ds_read_b128 v[156:159], v126 offset:64
	ds_read_b128 v[160:163], v127 offset:48384
	ds_read_b128 v[164:167], v127 offset:48448
	v_lshl_add_u32 v28, v94, 2, s30
	ds_read_b32 v116, v28
	ds_read_b128 v[40:43], v96
	v_lshl_add_u32 v61, v109, 2, s34
	s_waitcnt lgkmcnt(1)
	v_sub_f32_e32 v28, v115, v116
	v_mul_f32_e32 v28, 0x3fb8aa3b, v28
	v_exp_f32_e32 v60, v28
	ds_read_b128 v[44:47], v96 offset:64
	s_waitcnt lgkmcnt(0)
	v_mfma_f32_16x16x32_bf16 v[28:31], v[128:131], v[40:43], 0
	v_mfma_f32_16x16x32_bf16 v[28:31], v[132:135], v[44:47], v[28:31]
	v_sub_f32_e32 v32, v136, v116
	v_mul_f32_e32 v32, 0x3fb8aa3b, v32
	v_exp_f32_e32 v32, v32
	s_nop 2
	s_nop 1
	v_mul_f32_e32 v28, v28, v32
	v_cndmask_b32_e64 v32, v28, 0, s[60:61]
	v_sub_f32_e32 v28, v137, v116
	v_mul_f32_e32 v28, 0x3fb8aa3b, v28
	v_exp_f32_e32 v28, v28
	s_nop 0
	v_mul_f32_e32 v28, v29, v28
	v_cndmask_b32_e64 v33, 0, v28, s[62:63]
	v_sub_f32_e32 v28, v138, v116
	v_sub_f32_e32 v29, v139, v116
	v_mul_f32_e32 v28, 0x3fb8aa3b, v28
	v_mul_f32_e32 v29, 0x3fb8aa3b, v29
	v_exp_f32_e32 v28, v28
	v_exp_f32_e32 v29, v29
	s_nop 0
	v_pk_mul_f32 v[28:29], v[30:31], v[28:29]
	s_nop 0
	v_cvt_pk_bf16_f32 v28, v28, v29
	v_cndmask_b32_e64 v29, v28, 0, s[66:67]
	v_lshrrev_b32_e32 v28, 16, v28
	v_cndmask_b32_e64 v28, v28, 0, s[64:65]
	v_cvt_pk_bf16_f32 v30, v32, v33
	v_perm_b32 v31, v28, v29, s24
	ds_write_b64 v111, v[30:31] offset:27648
	v_mfma_f32_16x16x32_bf16 v[28:31], v[140:143], v[40:43], 0
	v_mfma_f32_16x16x32_bf16 v[28:31], v[144:147], v[44:47], v[28:31]
	v_mfma_f32_16x16x32_bf16 v[32:35], v[152:155], v[40:43], 0
	s_nop 4
	s_nop 1
	v_mul_f32_e64 v30, v60, v30
	v_mul_f32_e64 v31, v60, v31
	v_pk_mul_f32 v[28:29], v[60:61], v[28:29] op_sel_hi:[0,1]
	v_mfma_f32_16x16x32_bf16 v[32:35], v[148:151], v[44:47], v[32:35]
	v_sub_f32_e32 v36, v156, v116
	v_mul_f32_e32 v36, 0x3fb8aa3b, v36
	v_exp_f32_e32 v36, v36
	s_nop 2
	s_nop 1
	v_mul_f32_e32 v32, v32, v36
	v_cndmask_b32_e64 v36, v32, 0, s[68:69]
	v_sub_f32_e32 v32, v157, v116
	v_mul_f32_e32 v32, 0x3fb8aa3b, v32
	v_exp_f32_e32 v32, v32
	s_nop 0
	v_mul_f32_e32 v32, v33, v32
	v_cndmask_b32_e64 v37, 0, v32, s[70:71]
	v_sub_f32_e32 v32, v158, v116
	v_sub_f32_e32 v33, v159, v116
	v_mul_f32_e32 v32, 0x3fb8aa3b, v32
	v_mul_f32_e32 v33, 0x3fb8aa3b, v33
	v_exp_f32_e32 v32, v32
	v_exp_f32_e32 v33, v33
	s_nop 0
	v_pk_mul_f32 v[32:33], v[34:35], v[32:33]
	s_nop 0
	v_cvt_pk_bf16_f32 v32, v32, v33
	v_cndmask_b32_e64 v33, v32, 0, s[74:75]
	v_lshrrev_b32_e32 v32, 16, v32
	v_cndmask_b32_e64 v32, v32, 0, s[72:73]
	v_cvt_pk_bf16_f32 v34, v36, v37
	v_perm_b32 v35, v32, v33, s24
	ds_write_b64 v112, v[34:35] offset:27648
	v_mfma_f32_16x16x32_bf16 v[32:35], v[160:163], v[40:43], 0
	v_mfma_f32_16x16x32_bf16 v[32:35], v[164:167], v[44:47], v[32:35]
	v_mov_b32_e32 v36, 0
	v_mov_b32_e32 v37, 0
	v_mov_b32_e32 v38, 0
	v_mov_b32_e32 v39, 0
	s_nop 3
	v_pk_mul_f32 v[34:35], v[60:61], v[34:35] op_sel_hi:[0,1]
	v_pk_mul_f32 v[32:33], v[60:61], v[32:33] op_sel_hi:[0,1]
	s_and_saveexec_b64 s[76:77], s[48:49]
	s_cbranch_execz .LBB0_408
	v_add_u32_e32 v61, v104, v95
	ds_read_b128 v[36:39], v61 offset:57600
	s_waitcnt lgkmcnt(0)
	v_mfma_f32_16x16x32_bf16 v[36:39], v[36:39], v[40:43], 0
	ds_read_b128 v[40:43], v61 offset:57664
	v_mov_b32_e32 v61, v60
	s_waitcnt lgkmcnt(0)
	v_mfma_f32_16x16x32_bf16 v[36:39], v[40:43], v[44:47], v[36:39]
	v_mov_b32_e32 v40, v60
	v_mov_b32_e32 v41, v60
	s_nop 5
	v_pk_mul_f32 v[38:39], v[40:41], v[38:39]
	v_pk_mul_f32 v[36:37], v[60:61], v[36:37]

.LBB0_416:
	s_mul_i32 s36, s35, 0xa880
	s_add_i32 s36, s36, 0
	v_add_u32_e32 v60, s36, v95
	v_add_u32_e32 v117, v60, v108
	s_waitcnt lgkmcnt(0)
	s_barrier
	ds_read_b128 v[128:131], v117 offset:36864
	ds_read_b128 v[132:135], v117 offset:36928
	v_add_u32_e32 v125, v60, v110
	ds_read_b128 v[136:139], v125 offset:36864
	ds_read_b128 v[140:143], v125 offset:36928
	ds_read_b128 v[44:47], v96 offset:27648
	ds_read_b128 v[40:43], v96 offset:27712
	v_add_u32_e32 v61, v60, v110
	v_add3_u32 v60, s36, v103, v95
	s_waitcnt lgkmcnt(0)
	v_mfma_f32_16x16x32_bf16 v[28:31], v[128:131], v[44:47], v[28:31]
	v_mfma_f32_16x16x32_bf16 v[28:31], v[132:135], v[40:43], v[28:31]
	v_mfma_f32_16x16x32_bf16 v[32:35], v[136:139], v[44:47], v[32:35]
	v_mfma_f32_16x16x32_bf16 v[32:35], v[140:143], v[40:43], v[32:35]
	s_and_saveexec_b64 s[76:77], s[48:49]
	s_cbranch_execz .LBB0_418
	ds_read_b128 v[118:121], v60 offset:46080
	s_waitcnt lgkmcnt(0)
	v_mfma_f32_16x16x32_bf16 v[36:39], v[118:121], v[44:47], v[36:39]
	ds_read_b128 v[44:47], v60 offset:46144
	s_waitcnt lgkmcnt(0)
	v_mfma_f32_16x16x32_bf16 v[36:39], v[44:47], v[40:43], v[36:39]
	s_nop 7
	ds_write_b32 v113, v36
.LBB0_418:
	s_or_b64 exec, exec, s[76:77]
	s_xor_b32 s78, s35, 1
	s_mul_i32 s76, s35, 0x16c20
	s_mul_i32 s35, s78, 0x7b80
	s_add_i32 s77, s35, 0
	v_add_u32_e32 v36, s77, v79
	v_add_u32_e32 v36, v36, v80
	v_lshl_add_u32 v47, v94, 2, s31
	s_add_i32 s35, s17, 0xffffff00
	s_cmp_lt_u32 s29, 4
	s_cselect_b32 s29, s17, s35
	v_add_u32_e32 v122, s77, v198
	v_mov_b32_e32 v154, 0xbfb8aa3b
	ds_read_b32 v131, v122 offset:0
	ds_read_b32 v133, v122 offset:272
	ds_read_b32 v135, v122 offset:544
	ds_read_b32 v137, v122 offset:816
	ds_read_b32 v139, v122 offset:1088
	ds_read_b32 v141, v122 offset:1360
	s_waitcnt lgkmcnt(3)
	v_lshlrev_b32_e32 v130, 16, v131
	v_and_b32_e32 v131, 0xffff0000, v131
	v_lshlrev_b32_e32 v132, 16, v133
	v_and_b32_e32 v133, 0xffff0000, v133
	v_lshlrev_b32_e32 v134, 16, v135
	v_and_b32_e32 v135, 0xffff0000, v135
	s_waitcnt lgkmcnt(0)
	v_lshlrev_b32_e32 v136, 16, v137
	v_and_b32_e32 v137, 0xffff0000, v137
	v_lshlrev_b32_e32 v138, 16, v139
	v_and_b32_e32 v139, 0xffff0000, v139
	v_lshlrev_b32_e32 v140, 16, v141
	v_and_b32_e32 v141, 0xffff0000, v141
	v_pk_mul_f32 v[160:161], v[172:173], v[130:131]
	v_pk_mul_f32 v[162:163], v[172:173], v[132:133]
	v_pk_mul_f32 v[164:165], v[172:173], v[134:135]
	v_pk_mul_f32 v[166:167], v[172:173], v[136:137]
	v_pk_fma_f32 v[160:161], v[174:175], v[132:133], v[160:161]
	v_pk_fma_f32 v[162:163], v[174:175], v[134:135], v[162:163]
	v_pk_fma_f32 v[164:165], v[174:175], v[136:137], v[164:165]
	v_pk_fma_f32 v[166:167], v[174:175], v[138:139], v[166:167]
	v_pk_fma_f32 v[160:161], v[176:177], v[134:135], v[160:161]
	v_pk_fma_f32 v[162:163], v[176:177], v[136:137], v[162:163]
	v_pk_fma_f32 v[164:165], v[176:177], v[138:139], v[164:165]
	v_pk_fma_f32 v[166:167], v[176:177], v[140:141], v[166:167]
	v_pk_add_f32 v[160:161], v[178:179], v[160:161]
	v_pk_add_f32 v[162:163], v[178:179], v[162:163]
	v_pk_add_f32 v[164:165], v[178:179], v[164:165]
	v_pk_add_f32 v[166:167], v[178:179], v[166:167]
	v_pk_mul_f32 v[188:189], v[160:161], v[154:155] op_sel_hi:[1,0]
	v_pk_mul_f32 v[190:191], v[162:163], v[154:155] op_sel_hi:[1,0]
	v_pk_mul_f32 v[192:193], v[164:165], v[154:155] op_sel_hi:[1,0]
	v_pk_mul_f32 v[194:195], v[166:167], v[154:155] op_sel_hi:[1,0]
	v_exp_f32_e32 v188, v188
	v_exp_f32_e32 v190, v190
	v_exp_f32_e32 v192, v192
	v_exp_f32_e32 v194, v194
	v_exp_f32_e32 v189, v189
	v_exp_f32_e32 v191, v191
	v_exp_f32_e32 v193, v193
	v_exp_f32_e32 v195, v195
	v_pk_add_f32 v[188:189], v[188:189], 1.0 op_sel_hi:[1,0]
	v_pk_add_f32 v[190:191], v[190:191], 1.0 op_sel_hi:[1,0]
	v_pk_add_f32 v[192:193], v[192:193], 1.0 op_sel_hi:[1,0]
	v_pk_add_f32 v[194:195], v[194:195], 1.0 op_sel_hi:[1,0]
	v_rcp_f32_e32 v188, v188
	v_rcp_f32_e32 v190, v190
	v_rcp_f32_e32 v192, v192
	v_rcp_f32_e32 v194, v194
	v_rcp_f32_e32 v189, v189
	v_rcp_f32_e32 v191, v191
	v_rcp_f32_e32 v193, v193
	v_rcp_f32_e32 v195, v195
	v_pk_mul_f32 v[160:161], v[160:161], v[188:189]
	v_pk_mul_f32 v[162:163], v[162:163], v[190:191]
	v_pk_mul_f32 v[164:165], v[164:165], v[192:193]
	v_pk_mul_f32 v[166:167], v[166:167], v[194:195]
	v_cvt_pk_bf16_f32 v188, v160, v161
	v_cvt_pk_bf16_f32 v190, v162, v163
	v_cvt_pk_bf16_f32 v192, v164, v165
	v_cvt_pk_bf16_f32 v194, v166, v167
	ds_write_b32 v199, v188 offset:0
	ds_write_b32 v199, v190 offset:144
	ds_write_b32 v199, v192 offset:288
	ds_write_b32 v199, v194 offset:432
	s_waitcnt lgkmcnt(0)
	s_barrier
	ds_read_b32 v125, v102
	ds_read_b32 v126, v47
	v_add_u32_e32 v127, s76, v96
	ds_read_b128 v[128:131], v127 offset:18432
	ds_read_b128 v[132:135], v117 offset:36864
	ds_read_b128 v[136:139], v127 offset:18496
	ds_read_b128 v[140:143], v117 offset:36928
	ds_read_b128 v[144:147], v127 offset:18432
	ds_read_b128 v[148:151], v61 offset:36864
	ds_read_b128 v[152:155], v127 offset:18496
	ds_read_b128 v[156:159], v61 offset:36928
	v_add_u32_e32 v44, s29, v94
	s_cselect_b32 s29, 0xff, s22
	v_sub_u32_e32 v45, s29, v44
	s_waitcnt lgkmcnt(8)
	v_max_f32_e64 v46, |v125|, |v125|
	v_add_f32_e32 v47, v116, v126
	v_mul_f32_e32 v47, 0xbfb8aa3b, v47
	v_exp_f32_e32 v47, v47
	v_cndmask_b32_e64 v44, v45, v44, s[40:41]
	s_cselect_b32 s29, s16, s28
	v_add_u32_e32 v44, s29, v44
	v_max_f32_e32 v46, v46, v47
	v_rcp_f32_e32 v46, v46
	v_ashrrev_i32_e32 v45, 31, v44
	v_lshlrev_b64 v[44:45], 11, v[44:45]
	v_pk_mul_f32 v[28:29], v[28:29], v[46:47] op_sel_hi:[1,0]
	v_pk_mul_f32 v[30:31], v[30:31], v[46:47] op_sel_hi:[1,0]
	v_cvt_pk_bf16_f32 v28, v28, v29
	v_cvt_pk_bf16_f32 v29, v30, v31
	v_lshl_add_u64 v[30:31], v[58:59], 0, v[44:45]
	global_store_dwordx2 v[30:31], v[28:29], off offset:1024
	v_pk_mul_f32 v[28:29], v[32:33], v[46:47] op_sel_hi:[1,0]
	v_pk_mul_f32 v[32:33], v[34:35], v[46:47] op_sel_hi:[1,0]
	v_cvt_pk_bf16_f32 v28, v28, v29
	v_cvt_pk_bf16_f32 v29, v32, v33
	global_store_dwordx2 v[30:31], v[28:29], off offset:1056
	v_mov_b32_e32 v28, s30
	ds_read_b32 v30, v28 offset:252
	v_add_u32_e32 v31, s76, v96
	s_waitcnt lgkmcnt(0)
	v_sub_f32_e32 v28, v115, v30
	v_mul_f32_e32 v28, 0x3fb8aa3b, v28
	v_exp_f32_e32 v28, v28
	s_nop 0
	v_pk_mul_f32 v[26:27], v[26:27], v[28:29] op_sel_hi:[1,0]
	v_pk_mul_f32 v[24:25], v[24:25], v[28:29] op_sel_hi:[1,0]
	v_add_u32_e32 v29, v107, v108
	v_pk_mul_f32 v[18:19], v[18:19], v[28:29] op_sel_hi:[1,0]
	v_mfma_f32_16x16x32_bf16 v[24:27], v[128:131], v[132:135], v[24:27]
	v_pk_mul_f32 v[16:17], v[16:17], v[28:29] op_sel_hi:[1,0]
	v_mfma_f32_16x16x32_bf16 v[24:27], v[136:139], v[140:143], v[24:27]
	s_nop 7
	v_cvt_pk_bf16_f32 v32, v24, v25
	v_cvt_pk_bf16_f32 v33, v26, v27
	ds_write_b64 v29, v[32:33] offset:48384
	v_mfma_f32_16x16x32_bf16 v[16:19], v[144:147], v[148:151], v[16:19]
	v_add_u32_e32 v29, v107, v110
	v_mfma_f32_16x16x32_bf16 v[16:19], v[152:155], v[156:159], v[16:19]
	s_nop 7
	v_cvt_pk_bf16_f32 v32, v16, v17
	v_cvt_pk_bf16_f32 v33, v18, v19
	ds_write_b64 v29, v[32:33] offset:48384
	s_and_saveexec_b64 s[76:77], s[48:49]
	s_cbranch_execz .LBB0_405
	v_mov_b32_e32 v32, v28
	v_mov_b32_e32 v33, v28
	v_pk_mul_f32 v[22:23], v[32:33], v[22:23]
	ds_read_b128 v[32:35], v31 offset:18432
	ds_read_b128 v[44:47], v60 offset:46080
	v_mov_b32_e32 v29, v28
	v_pk_mul_f32 v[20:21], v[28:29], v[20:21]
	s_waitcnt lgkmcnt(0)
	s_nop 0
	v_mfma_f32_16x16x32_bf16 v[20:23], v[32:35], v[44:47], v[20:23]
	ds_read_b128 v[32:35], v31 offset:18496
	ds_read_b128 v[44:47], v60 offset:46144
	s_waitcnt lgkmcnt(0)
	v_mfma_f32_16x16x32_bf16 v[20:23], v[32:35], v[44:47], v[20:23]
	s_nop 7
	v_cvt_pk_bf16_f32 v28, v20, v21
	v_cvt_pk_bf16_f32 v29, v22, v23
	ds_write_b64 v114, v[28:29] offset:57600
	s_branch .LBB0_405

.LBB0_441:
	s_or_b64 exec, exec, s[52:53]
	v_cndmask_b32_e64 v81, 64, -1, s[46:47]
	v_add_u32_e32 v13, 64, v81
	v_sub_u32_e32 v14, 0xbf, v81
	v_cndmask_b32_e64 v13, v14, v13, s[40:41]
	v_add_u32_e32 v13, s28, v13
	v_mul_lo_u32 v14, v13, s20
	v_mov_b32_e32 v15, v169
	v_lshl_add_u64 v[14:15], s[12:13], 0, v[14:15]
	v_mov_b32_e32 v13, v169
	v_lshl_add_u64 v[12:13], v[12:13], 1, v[14:15]
	v_or_b32_e32 v14, 64, v62
	v_xor_b32_e32 v15, 0xbf, v62
	v_cndmask_b32_e64 v14, v15, v14, s[40:41]
	v_or_b32_e32 v14, s28, v14
	s_and_b64 s[16:17], s[40:41], exec
	s_mov_b32 s9, 0xab34000
	v_mul_lo_u32 v14, v14, s21
	v_mov_b32_e32 v15, v169
	s_cselect_b32 s9, s9, 0xed34000
	v_readlane_b32 s16, v254, 53
	v_lshl_add_u64 v[14:15], s[14:15], 0, v[14:15]
	s_add_u32 s16, s16, s9
	v_mov_b32_e32 v57, v169
	v_lshl_add_u64 v[14:15], v[14:15], 0, s[84:85]
	s_mov_b32 s9, s85
	v_ashrrev_i32_e32 v37, 6, v17
	v_lshl_add_u64 v[12:13], v[12:13], 0, v[56:57]
	v_lshl_add_u64 v[18:19], v[14:15], 0, s[8:9]
	global_load_dwordx4 v[12:15], v[12:13], off
	s_nop 0
	global_load_dword v88, v[18:19], off offset:128
	v_lshlrev_b32_e32 v83, 1, v62
	v_lshl_or_b32 v18, v37, 3, 1
	s_movk_i32 s9, 0xc80
	v_add_u32_e32 v16, 0, v83
	v_mul_lo_u32 v86, v18, s29
	s_movk_i32 s35, 0x90
	v_mul_lo_u32 v82, v37, s9
	s_movk_i32 s9, 0x480
	v_add_u32_e32 v61, v16, v86
	v_mul_lo_u32 v97, v18, s35
	v_mul_lo_u32 v95, v37, s9
	v_add_u32_e32 v100, 0x90, v97
	v_add_u32_e32 v102, 0x120, v97
	v_add_u32_e32 v101, 0x4b0, v61
	v_add_u32_e32 v104, 0x1b0, v97
	v_add_u32_e32 v107, 0x240, v97
	v_add_u32_e32 v108, 0x2d0, v97
	v_add_u32_e32 v109, 0x360, v97
	s_waitcnt lgkmcnt(0)
	s_barrier
	v_add_u32_e32 v39, v16, v82
	v_add_u32_e32 v84, v16, v95
	v_add_u32_e32 v87, v16, v97
	v_add_u32_e32 v98, 0x190, v61
	v_add_u32_e32 v89, v16, v100
	v_add_u32_e32 v99, 0x320, v61
	v_add_u32_e32 v90, v16, v102
	v_add_u32_e32 v94, v16, v104
	v_add_u32_e32 v103, 0x640, v61
	v_add_u32_e32 v114, v16, v107
	v_add_u32_e32 v105, 0x7d0, v61
	v_add_u32_e32 v91, v16, v108
	v_add_u32_e32 v106, 0x960, v61
	v_add_u32_e32 v96, v16, v109
	ds_read_u16 v16, v101 offset:65440
	ds_read_u16 v18, v103 offset:65440
	ds_read_u16 v92, v105 offset:65440
	ds_read_u16 v19, v106 offset:65440
	ds_read_u16 v112, v99 offset:65440
	s_waitcnt lgkmcnt(4)
	v_lshlrev_b32_e32 v54, 16, v16
	ds_read_u16 v115, v98 offset:65440
	ds_read_u16 v16, v61 offset:65440
	ds_read_u16 v20, v39 offset:65440
	ds_read_u16 v41, v39 offset:64640
	s_waitcnt vmcnt(5)
	ds_read_u16 v21, v39 offset:65040
	v_mov_b32_e32 v45, v44
	s_waitcnt lgkmcnt(3)
	v_lshlrev_b32_e32 v51, 16, v16
	s_waitcnt lgkmcnt(2)
	v_lshlrev_b32_e32 v50, 16, v20
	s_waitcnt lgkmcnt(1)
	v_lshlrev_b32_e32 v48, 16, v41
	s_waitcnt lgkmcnt(0)
	v_lshlrev_b32_e32 v49, 16, v21
	v_mov_b32_e32 v16, v43
	v_pk_mov_b32 v[52:53], v[48:49], v[50:51] op_sel:[1,0]
	v_mov_b32_e32 v41, v40
	v_pk_mul_f32 v[52:53], v[16:17], v[52:53] op_sel_hi:[0,1]
	v_pk_fma_f32 v[48:49], v[40:41], v[48:49], v[52:53] op_sel_hi:[0,1,1]
	v_pk_fma_f32 v[48:49], v[42:43], v[50:51], v[48:49] op_sel_hi:[0,1,1]
	v_pk_add_f32 v[48:49], v[44:45], v[48:49] op_sel_hi:[0,1]
	v_mul_f32_e32 v52, 0xbfb8aa3b, v48
	v_mul_f32_e32 v53, 0xbfb8aa3b, v49
	v_exp_f32_e32 v52, v52
	v_exp_f32_e32 v53, v53
	v_lshlrev_b32_e32 v113, 16, v112
	v_lshlrev_b32_e32 v112, 16, v115
	v_add_f32_e32 v52, 1.0, v52
	v_add_f32_e32 v53, 1.0, v53
	v_rcp_f32_e32 v52, v52
	v_rcp_f32_e32 v53, v53
	v_lshlrev_b32_e32 v55, 16, v18
	v_lshlrev_b32_e32 v111, 16, v92
	v_mov_b32_e32 v110, v55
	v_pk_mul_f32 v[48:49], v[48:49], v[52:53]
	v_pk_mov_b32 v[52:53], v[50:51], v[112:113] op_sel:[1,0]
	v_cvt_pk_bf16_f32 v92, v48, s0
	v_pk_mul_f32 v[52:53], v[16:17], v[52:53] op_sel_hi:[0,1]
	v_pk_fma_f32 v[50:51], v[40:41], v[50:51], v[52:53] op_sel_hi:[0,1,1]
	v_pk_fma_f32 v[50:51], v[42:43], v[112:113], v[50:51] op_sel_hi:[0,1,1]
	v_pk_add_f32 v[50:51], v[44:45], v[50:51] op_sel_hi:[0,1]
	v_mul_f32_e32 v52, 0xbfb8aa3b, v50
	v_mul_f32_e32 v53, 0xbfb8aa3b, v51
	v_exp_f32_e32 v52, v52
	v_exp_f32_e32 v53, v53
	ds_write_b16 v84, v92 offset:9216
	v_cvt_pk_bf16_f32 v92, v49, s0
	v_add_f32_e32 v52, 1.0, v52
	v_add_f32_e32 v53, 1.0, v53
	v_rcp_f32_e32 v52, v52
	v_rcp_f32_e32 v53, v53
	ds_write_b16 v87, v92 offset:9216
	v_lshlrev_b32_e32 v93, 16, v19
	v_readlane_b32 s17, v254, 54
	v_pk_mul_f32 v[50:51], v[50:51], v[52:53]
	v_pk_mov_b32 v[52:53], v[112:113], v[54:55] op_sel:[1,0]
	v_cvt_pk_bf16_f32 v115, v50, s0
	v_pk_mul_f32 v[52:53], v[16:17], v[52:53] op_sel_hi:[0,1]
	v_pk_fma_f32 v[52:53], v[40:41], v[112:113], v[52:53] op_sel_hi:[0,1,1]
	v_pk_fma_f32 v[52:53], v[42:43], v[54:55], v[52:53] op_sel_hi:[0,1,1]
	v_pk_add_f32 v[52:53], v[44:45], v[52:53] op_sel_hi:[0,1]
	v_mul_f32_e32 v92, 0xbfb8aa3b, v52
	v_exp_f32_e32 v92, v92
	v_mul_f32_e32 v112, 0xbfb8aa3b, v53
	v_exp_f32_e32 v113, v112
	ds_write_b16 v89, v115 offset:9216
	v_add_f32_e32 v92, 1.0, v92
	v_rcp_f32_e32 v112, v92
	v_add_f32_e32 v92, 1.0, v113
	v_rcp_f32_e32 v113, v92
	v_cvt_pk_bf16_f32 v92, v51, s0
	ds_write_b16 v90, v92 offset:9216
	v_mov_b32_e32 v92, v111
	v_pk_mul_f32 v[110:111], v[16:17], v[110:111] op_sel_hi:[0,1]
	v_pk_fma_f32 v[54:55], v[40:41], v[54:55], v[110:111] op_sel_hi:[0,1,1]
	v_pk_fma_f32 v[54:55], v[42:43], v[92:93], v[54:55] op_sel_hi:[0,1,1]
	v_pk_add_f32 v[54:55], v[44:45], v[54:55] op_sel_hi:[0,1]
	v_mul_f32_e32 v16, 0xbfb8aa3b, v54
	v_exp_f32_e32 v16, v16
	v_mul_f32_e32 v92, 0xbfb8aa3b, v55
	v_exp_f32_e32 v93, v92
	v_pk_mul_f32 v[52:53], v[52:53], v[112:113]
	v_add_f32_e32 v16, 1.0, v16
	v_rcp_f32_e32 v92, v16
	v_add_f32_e32 v16, 1.0, v93
	v_rcp_f32_e32 v93, v16
	v_cvt_pk_bf16_f32 v110, v52, s0
	v_cvt_pk_bf16_f32 v16, v53, s0
	ds_write_b16 v94, v110 offset:9216
	v_pk_mul_f32 v[54:55], v[54:55], v[92:93]
	ds_write_b16 v114, v16 offset:9216
	v_cvt_pk_bf16_f32 v16, v54, s0
	v_lshlrev_b32_e32 v35, 5, v37
	s_addc_u32 s17, s17, 0
	s_add_i32 s9, 0, 0x16520
	ds_write_b16 v91, v16 offset:9216
	v_cvt_pk_bf16_f32 v16, v55, s0
	v_add_u32_e32 v46, 0xfc00, v39
	v_add_u32_e32 v85, s9, v35
	ds_write_b16 v96, v16 offset:9216
	ds_read_b128 v[18:21], v85
	ds_read_u16 v16, v39 offset:65168
	ds_read_u16 v46, v46 offset:1056
	ds_read_u16 v92, v39 offset:64768
	v_add_u32_e32 v110, 0x10020, v61
	v_add_u32_e32 v111, 0x101b0, v61
	s_waitcnt lgkmcnt(2)
	v_lshlrev_b32_e32 v16, 16, v16
	s_waitcnt lgkmcnt(1)
	v_lshlrev_b32_e32 v46, 16, v46
	s_waitcnt lgkmcnt(0)
	v_lshlrev_b32_e32 v92, 16, v92
	v_mul_f32_e32 v92, v63, v92
	v_fmac_f32_e32 v92, v64, v16
	v_fmac_f32_e32 v92, v65, v46
	v_add_f32_e32 v92, v66, v92
	v_mul_f32_e32 v93, 0xbfb8aa3b, v92
	v_exp_f32_e32 v93, v93
	v_add_u32_e32 v112, 0x10340, v61
	v_add_u32_e32 v113, 0x104d0, v61
	v_add_u32_e32 v115, 0x10660, v61
	v_add_f32_e32 v93, 1.0, v93
	v_rcp_f32_e32 v93, v93
	ds_read_u16 v110, v110
	ds_read_u16 v111, v111
	ds_read_u16 v112, v112
	ds_read_u16 v113, v113
	ds_read_u16 v115, v115
	v_mul_f32_e32 v16, v63, v16
	s_waitcnt lgkmcnt(4)
	v_lshlrev_b32_e32 v110, 16, v110
	v_fmac_f32_e32 v16, v64, v46
	v_fmac_f32_e32 v16, v65, v110
	v_add_f32_e32 v16, v66, v16
	v_mul_f32_e32 v92, v92, v93
	v_mul_f32_e32 v116, 0xbfb8aa3b, v16
	v_cvt_pk_bf16_f32 v92, v92, s0
	v_mul_f32_e32 v93, v64, v110
	v_exp_f32_e32 v116, v116
	ds_write_b16 v84, v92
	s_waitcnt lgkmcnt(4)
	v_lshlrev_b32_e32 v92, 16, v111
	v_fmac_f32_e32 v93, v63, v46
	v_fmac_f32_e32 v93, v65, v92
	v_add_f32_e32 v46, v66, v93
	s_waitcnt lgkmcnt(3)
	v_lshlrev_b32_e32 v111, 16, v112
	v_mul_f32_e32 v112, v64, v92
	v_mul_f32_e32 v93, 0xbfb8aa3b, v46
	v_fmac_f32_e32 v112, v63, v110
	v_add_f32_e32 v116, 1.0, v116
	v_exp_f32_e32 v93, v93
	v_fmac_f32_e32 v112, v65, v111
	v_rcp_f32_e32 v116, v116
	v_add_f32_e32 v110, v66, v112
	v_mul_f32_e32 v112, 0xbfb8aa3b, v110
	v_exp_f32_e32 v112, v112
	v_add_f32_e32 v93, 1.0, v93
	v_mul_f32_e32 v16, v16, v116
	v_rcp_f32_e32 v93, v93
	v_cvt_pk_bf16_f32 v16, v16, s0
	ds_write_b16 v87, v16
	v_add_f32_e32 v16, 1.0, v112
	v_rcp_f32_e32 v16, v16
	v_mul_f32_e32 v46, v46, v93
	v_cvt_pk_bf16_f32 v46, v46, s0
	ds_write_b16 v89, v46
	s_waitcnt lgkmcnt(4)
	v_lshlrev_b32_e32 v46, 16, v113
	v_mul_f32_e32 v16, v110, v16
	v_mul_f32_e32 v89, v64, v111
	v_mul_f32_e32 v110, v64, v46
	v_fmac_f32_e32 v89, v63, v92
	s_waitcnt lgkmcnt(3)
	v_lshlrev_b32_e32 v93, 16, v115
	v_fmac_f32_e32 v110, v63, v111
	v_fmac_f32_e32 v89, v65, v46
	v_fmac_f32_e32 v110, v65, v93
	v_add_f32_e32 v89, v66, v89
	v_add_f32_e32 v110, v66, v110
	v_mul_f32_e32 v92, 0xbfb8aa3b, v89
	v_mul_f32_e32 v111, 0xbfb8aa3b, v110
	v_exp_f32_e32 v92, v92
	v_exp_f32_e32 v111, v111
	v_cvt_pk_bf16_f32 v16, v16, s0
	ds_write_b16 v90, v16
	v_add_f32_e32 v92, 1.0, v92
	v_add_f32_e32 v16, 1.0, v111
	v_rcp_f32_e32 v92, v92
	v_rcp_f32_e32 v16, v16
	v_pk_mul_f32 v[18:19], v[18:19], v[48:49]
	v_pk_mul_f32 v[20:21], v[20:21], v[50:51]
	v_mul_f32_e32 v89, v89, v92
	v_mul_f32_e32 v16, v110, v16
	v_cvt_pk_bf16_f32 v89, v89, s0
	v_cvt_pk_bf16_f32 v16, v16, s0
	ds_write_b16 v94, v89
	ds_write_b16 v114, v16
	v_add_u32_e32 v16, 0x107f0, v61
	ds_read_u16 v16, v16
	v_or_b32_e32 v114, 16, v35
	v_add_u32_e32 v89, s9, v114
	ds_read_b128 v[110:113], v89
	v_cvt_pk_bf16_f32 v18, v18, v19
	s_waitcnt lgkmcnt(1)
	v_lshlrev_b32_e32 v94, 16, v16
	v_mul_f32_e32 v16, v64, v93
	v_fmac_f32_e32 v16, v63, v46
	v_fmac_f32_e32 v16, v65, v94
	v_add_f32_e32 v92, v66, v16
	v_mul_f32_e32 v16, 0xbfb8aa3b, v92
	v_exp_f32_e32 v46, v16
	v_mul_f32_e32 v94, v64, v94
	v_fmac_f32_e32 v94, v63, v93
	s_waitcnt lgkmcnt(0)
	v_pk_mul_f32 v[50:51], v[112:113], v[54:55]
	v_add_f32_e32 v46, 1.0, v46
	v_rcp_f32_e32 v117, v46
	v_cndmask_b32_e64 v46, 0, v33, s[40:41]
	v_cvt_pk_bf16_f32 v19, v20, v21
	v_cvt_pk_bf16_f32 v21, v50, v51
	v_mul_f32_e32 v33, v92, v117
	v_cvt_pk_bf16_f32 v33, v33, s0
	ds_write_b16 v91, v33
	v_add_u32_e32 v33, 0x10980, v61
	ds_read_u16 v33, v33
	s_movk_i32 s34, 0xff72
	v_and_b32_e32 v115, 32, v35
	v_lshrrev_b32_e32 v116, 4, v62
	v_cmp_gt_u32_e64 s[46:47], 47, v59
	s_waitcnt lgkmcnt(0)
	v_lshlrev_b32_e32 v33, 16, v33
	v_fmac_f32_e32 v94, v65, v33
	v_add_f32_e32 v33, v66, v94
	v_mul_f32_e32 v93, 0xbfb8aa3b, v33
	v_exp_f32_e32 v117, v93
	s_lshl_b32 s30, s30, 13
	v_cmp_eq_u32_e64 s[74:75], 1, v47
	v_mov_b32_e32 v16, 0
	v_add_f32_e32 v48, 1.0, v117
	v_rcp_f32_e32 v117, v48
	v_pk_mul_f32 v[48:49], v[110:111], v[52:53]
	s_mov_b32 s29, 0
	v_cvt_pk_bf16_f32 v20, v48, v49
	v_mul_f32_e32 v33, v33, v117
	v_cvt_pk_bf16_f32 v33, v33, s0
	ds_write_b16 v96, v33
	v_mad_u32_u24 v33, v62, s35, 0
	v_lshl_add_u32 v49, v37, 4, v33
	ds_write_b128 v49, v[18:21] offset:27648
	v_mad_i32_i24 v18, v62, s34, v33
	v_add_u32_e32 v95, v18, v95
	s_add_i32 s34, 0, 0x16420
	v_add_u32_e32 v97, v18, v97
	v_add_u32_e32 v48, v18, v100
	v_add_u32_e32 v52, v18, v102
	v_add_u32_e32 v110, v18, v104
	v_add_u32_e32 v107, v18, v107
	v_add_u32_e32 v108, v18, v108
	v_add_u32_e32 v109, v18, v109
	ds_read_u16 v18, v101 offset:65312
	ds_read_u16 v19, v103 offset:65312
	ds_read_u16 v102, v105 offset:65312
	ds_read_u16 v20, v106 offset:65312
	ds_read_u16 v104, v99 offset:65312
	v_add_u32_e32 v96, s34, v35
	s_waitcnt lgkmcnt(4)
	v_lshlrev_b32_e32 v50, 16, v18
	ds_read_u16 v106, v98 offset:65312
	ds_read_u16 v18, v61 offset:65312
	ds_read_u16 v21, v39 offset:65312
	ds_read_u16 v33, v39 offset:64512
	ds_read_u16 v35, v39 offset:64912
	v_mov_b32_e32 v37, v36
	s_waitcnt lgkmcnt(3)
	v_lshlrev_b32_e32 v55, 16, v18
	s_waitcnt lgkmcnt(2)
	v_lshlrev_b32_e32 v54, 16, v21
	s_waitcnt lgkmcnt(1)
	v_lshlrev_b32_e32 v98, 16, v33
	s_waitcnt lgkmcnt(0)
	v_lshlrev_b32_e32 v99, 16, v35
	v_mov_b32_e32 v35, v34
	v_pk_mov_b32 v[100:101], v[98:99], v[54:55] op_sel:[1,0]
	v_mov_b32_e32 v33, v32
	v_pk_mul_f32 v[100:101], v[34:35], v[100:101] op_sel_hi:[0,1]
	v_pk_fma_f32 v[98:99], v[32:33], v[98:99], v[100:101] op_sel_hi:[0,1,1]
	v_pk_fma_f32 v[98:99], v[36:37], v[54:55], v[98:99] op_sel_hi:[0,1,1]
	v_mov_b32_e32 v39, v38
	v_pk_add_f32 v[98:99], v[38:39], v[98:99] op_sel_hi:[0,1]
	v_mul_f32_e32 v61, 0xbfb8aa3b, v98
	v_exp_f32_e32 v61, v61
	v_mul_f32_e32 v100, 0xbfb8aa3b, v99
	v_exp_f32_e32 v100, v100
	v_lshlrev_b32_e32 v101, 16, v102
	v_add_f32_e32 v61, 1.0, v61
	v_rcp_f32_e32 v102, v61
	v_add_f32_e32 v61, 1.0, v100
	v_rcp_f32_e32 v103, v61
	v_lshlrev_b32_e32 v105, 16, v104
	v_lshlrev_b32_e32 v104, 16, v106
	v_lshlrev_b32_e32 v51, 16, v19
	v_pk_mul_f32 v[98:99], v[98:99], v[102:103]
	v_pk_mov_b32 v[102:103], v[54:55], v[104:105] op_sel:[1,0]
	v_cvt_pk_bf16_f32 v61, v98, s0
	v_pk_mul_f32 v[102:103], v[34:35], v[102:103] op_sel_hi:[0,1]
	v_pk_fma_f32 v[54:55], v[32:33], v[54:55], v[102:103] op_sel_hi:[0,1,1]
	v_pk_fma_f32 v[54:55], v[36:37], v[104:105], v[54:55] op_sel_hi:[0,1,1]
	v_pk_add_f32 v[54:55], v[38:39], v[54:55] op_sel_hi:[0,1]
	v_mul_f32_e32 v102, 0xbfb8aa3b, v54
	v_exp_f32_e32 v102, v102
	v_mul_f32_e32 v103, 0xbfb8aa3b, v55
	v_exp_f32_e32 v103, v103
	ds_write_b16 v95, v61 offset:55296
	v_add_f32_e32 v61, 1.0, v102
	v_lshlrev_b32_e32 v53, 16, v20
	ds_read_b128 v[18:21], v96
	v_rcp_f32_e32 v102, v61
	v_add_f32_e32 v61, 1.0, v103
	v_rcp_f32_e32 v103, v61
	v_cvt_pk_bf16_f32 v61, v99, s0
	s_waitcnt lgkmcnt(0)
	v_pk_mul_f32 v[98:99], v[18:19], v[98:99]
	ds_write_b16 v97, v61 offset:55296
	v_pk_mul_f32 v[18:19], v[54:55], v[102:103]
	v_mov_b32_e32 v100, v51
	v_cvt_pk_bf16_f32 v54, v18, s0
	ds_write_b16 v48, v54 offset:55296
	v_pk_mov_b32 v[54:55], v[104:105], v[50:51] op_sel:[1,0]
	v_add_u32_e32 v111, s34, v114
	v_pk_mul_f32 v[54:55], v[34:35], v[54:55] op_sel_hi:[0,1]
	v_pk_fma_f32 v[54:55], v[32:33], v[104:105], v[54:55] op_sel_hi:[0,1,1]
	v_pk_fma_f32 v[54:55], v[36:37], v[50:51], v[54:55] op_sel_hi:[0,1,1]
	v_pk_add_f32 v[54:55], v[38:39], v[54:55] op_sel_hi:[0,1]
	v_mul_f32_e32 v48, 0xbfb8aa3b, v54
	v_exp_f32_e32 v48, v48
	v_mul_f32_e32 v61, 0xbfb8aa3b, v55
	v_exp_f32_e32 v61, v61
	v_cvt_pk_bf16_f32 v104, v19, s0
	ds_write_b16 v52, v104 offset:55296
	v_mov_b32_e32 v52, v101
	v_pk_mul_f32 v[100:101], v[34:35], v[100:101] op_sel_hi:[0,1]
	v_add_f32_e32 v48, 1.0, v48
	v_pk_fma_f32 v[50:51], v[32:33], v[50:51], v[100:101] op_sel_hi:[0,1,1]
	v_rcp_f32_e32 v102, v48
	v_add_f32_e32 v48, 1.0, v61
	v_pk_fma_f32 v[50:51], v[36:37], v[52:53], v[50:51] op_sel_hi:[0,1,1]
	v_rcp_f32_e32 v103, v48
	v_pk_add_f32 v[50:51], v[38:39], v[50:51] op_sel_hi:[0,1]
	v_mul_f32_e32 v52, 0xbfb8aa3b, v50
	v_exp_f32_e32 v52, v52
	v_mul_f32_e32 v53, 0xbfb8aa3b, v51
	v_exp_f32_e32 v53, v53
	v_pk_mul_f32 v[54:55], v[54:55], v[102:103]
	v_pk_mul_f32 v[104:105], v[20:21], v[18:19]
	v_cvt_pk_bf16_f32 v48, v54, s0
	ds_write_b16 v110, v48 offset:55296
	v_add_f32_e32 v48, 1.0, v52
	ds_read_b128 v[18:21], v111
	v_rcp_f32_e32 v52, v48
	v_add_f32_e32 v48, 1.0, v53
	v_rcp_f32_e32 v53, v48
	v_cvt_pk_bf16_f32 v48, v55, s0
	s_waitcnt lgkmcnt(0)
	v_pk_mul_f32 v[54:55], v[18:19], v[54:55]
	ds_write_b16 v107, v48 offset:55296
	v_pk_mul_f32 v[18:19], v[50:51], v[52:53]
	v_add_u32_e32 v89, 0x190, v86
	v_cvt_pk_bf16_f32 v48, v18, s0
	v_pk_mul_f32 v[50:51], v[20:21], v[18:19]
	ds_write_b16 v108, v48 offset:55296
	v_cvt_pk_bf16_f32 v48, v19, s0
	v_cvt_pk_bf16_f32 v18, v98, v99
	v_cvt_pk_bf16_f32 v19, v104, v105
	v_cvt_pk_bf16_f32 v20, v54, v55
	v_cvt_pk_bf16_f32 v21, v50, v51
	ds_write_b16 v109, v48 offset:55296
	ds_write_b128 v49, v[18:21] offset:18432
	v_ashrrev_i32_e32 v18, 3, v17
	v_and_b32_e32 v18, -16, v18
	v_or_b32_e32 v98, v18, v58
	v_mul_lo_u32 v19, v98, s35
	v_add_u32_e32 v20, 0, v19
	v_lshlrev_b32_e32 v19, 2, v62
	v_add_u32_e32 v101, s34, v19
	s_add_i32 s34, 0, 0x16320
	v_and_b32_e32 v17, 48, v17
	v_add_u32_e32 v102, s34, v19
	v_add_u32_e32 v103, s9, v19
	v_mov_b32_e32 v19, 0x6590
	v_add_u32_e32 v99, v20, v17
	v_add_u32_e32 v100, 0, v17
	v_lshlrev_b32_e32 v17, 2, v116
	v_cndmask_b32_e64 v105, v19, 0, s[46:47]
	v_lshlrev_b32_e32 v19, 3, v116
	v_lshlrev_b32_e32 v18, 1, v18
	v_add3_u32 v106, 0, v19, v18
	v_or_b32_e32 v18, v115, v58
	v_or_b32_e32 v48, v115, v17
	v_mul_u32_u24_e32 v107, 0x90, v18
	v_or_b32_e32 v18, 3, v48
	v_or_b32_e32 v19, 2, v48
	v_cmp_gt_i32_e64 s[62:63], v18, v98
	v_or_b32_e32 v18, 16, v115
	v_cmp_gt_i32_e64 s[64:65], v19, v98
	v_or_b32_e32 v19, v18, v58
	v_or_b32_e32 v17, v18, v17
	v_mul_u32_u24_e32 v108, 0x90, v19
	v_or_b32_e32 v18, 3, v17
	v_or_b32_e32 v19, 2, v17
	v_cmp_gt_i32_e64 s[70:71], v18, v98
	v_cmp_gt_i32_e64 s[72:73], v19, v98
	v_lshl_add_u64 v[18:19], s[12:13], 0, v[168:169]
	v_lshl_add_u64 v[50:51], v[18:19], 0, v[22:23]
	v_lshl_add_u64 v[18:19], s[12:13], 0, v[24:25]
	v_lshl_add_u64 v[52:53], v[18:19], 0, v[26:27]
	v_lshl_add_u64 v[18:19], s[12:13], 0, v[28:29]
	v_lshl_add_u64 v[54:55], v[18:19], 0, v[30:31]
	v_cndmask_b32_e64 v18, v118, v119, s[74:75]
	s_add_u32 s9, s14, s84
	v_or_b32_e32 v18, s76, v18
	v_mov_b32_e32 v19, s77
	s_addc_u32 s34, s15, 0
	v_cndmask_b32_e32 v18, v18, v19, vcc
	s_add_u32 s76, s9, s8
	v_lshlrev_b32_e32 v168, 1, v18
	s_addc_u32 s77, s34, 0
	s_lshl_b32 s8, s31, 1
	v_lshlrev_b32_e32 v21, 1, v48
	v_cmp_gt_i32_e64 s[66:67], v17, v98
	v_cmp_lt_i32_e64 s[68:69], v17, v98
	v_lshlrev_b32_e32 v17, 1, v17
	v_lshl_add_u64 v[18:19], s[12:13], 0, v[168:169]
	s_add_u32 s8, s16, s8
	v_add_u32_e32 v90, 0x320, v86
	v_add_u32_e32 v91, 0x4b0, v86
	v_add_u32_e32 v92, 0x640, v86
	v_add_u32_e32 v93, 0x7d0, v86
	v_add_u32_e32 v94, 0x960, v86
	v_cndmask_b32_e64 v104, 64, -1, s[46:47]
	v_cmp_eq_u32_e64 s[46:47], 0, v58
	v_cmp_lt_u32_e64 s[48:49], 1, v58
	v_cmp_lt_u32_e64 s[50:51], 3, v58
	v_cmp_lt_u32_e64 s[52:53], 7, v58
	v_cmp_eq_u32_e64 s[54:55], 0, v60
	v_cmp_lt_u32_e64 s[56:57], 31, v62
	v_cmp_gt_i32_e64 s[58:59], v48, v98
	v_cmp_lt_i32_e64 s[60:61], v48, v98
	v_lshl_add_u64 v[56:57], v[18:19], 0, v[56:57]
	v_mov_b32_e32 v47, v46
	v_mov_b32_e32 v58, v43
	v_mov_b32_e32 v59, v42
	s_addc_u32 s9, s17, 0
	v_lshlrev_b32_e32 v168, 1, v48
	v_add_u32_e32 v109, v20, v21
	v_add_u32_e32 v110, v20, v17
	s_mov_b32 s35, 0
	v_mov_b32_e32 v17, v16
	v_mov_b32_e32 v18, v16
	v_mov_b32_e32 v19, v16
	v_mov_b32_e32 v20, v16
	v_mov_b32_e32 v21, v16
	v_mov_b32_e32 v22, v16
	v_mov_b32_e32 v23, v16
	s_waitcnt lgkmcnt(0)
	s_barrier
	v_lshrrev_b32_e32 v196, 5, v171
	v_and_b32_e32 v197, 31, v171
	v_lshlrev_b32_e32 v196, 2, v196
	v_mul_u32_u24_e32 v198, 0x190, v196
	v_lshl_add_u32 v198, v197, 2, v198
	v_add_u32_e32 v198, 0xfc00, v198
	v_mul_u32_u24_e32 v199, 0x90, v196
	v_lshl_add_u32 v199, v197, 2, v199
	v_mul_u32_u24_e32 v200, 0x120, v197
	v_lshl_add_u32 v200, v196, 1, v200
	v_lshlrev_b32_e32 v201, 2, v196
	v_add_u32_e32 v201, 0x16520, v201
	v_lshlrev_b32_e32 v202, 3, v197
	v_add_u32_e32 v203, 4, v202
	ds_bpermute_b32 v172, v202, v32
	ds_bpermute_b32 v173, v203, v32
	ds_bpermute_b32 v174, v202, v34
	ds_bpermute_b32 v175, v203, v34
	ds_bpermute_b32 v176, v202, v36
	ds_bpermute_b32 v177, v203, v36
	ds_bpermute_b32 v178, v202, v38
	ds_bpermute_b32 v179, v203, v38
	ds_bpermute_b32 v180, v202, v40
	ds_bpermute_b32 v181, v203, v40
	ds_bpermute_b32 v182, v202, v43
	ds_bpermute_b32 v183, v203, v43
	ds_bpermute_b32 v184, v202, v42
	ds_bpermute_b32 v185, v203, v42
	ds_bpermute_b32 v186, v202, v44
	ds_bpermute_b32 v187, v203, v44
	ds_bpermute_b32 v188, v202, v63
	ds_bpermute_b32 v189, v203, v63
	ds_bpermute_b32 v190, v202, v64
	ds_bpermute_b32 v191, v203, v64
	ds_bpermute_b32 v192, v202, v65
	ds_bpermute_b32 v193, v203, v65
	ds_bpermute_b32 v194, v202, v66
	ds_bpermute_b32 v195, v203, v66
	s_waitcnt lgkmcnt(0)
	s_branch .LBB0_443
.LBB0_442:
	s_mul_i32 s16, s34, 0x18920
	s_xor_b32 s74, s34, 1
	s_mul_i32 s17, s74, 0x6b00
	s_add_i32 s34, s17, 0
	v_mul_f32_e32 v61, 0x3fb8aa3b, v61
	v_exp_f32_e32 v112, v61
	v_ashrrev_i32_e32 v61, 31, v60
	v_lshlrev_b64 v[60:61], 11, v[60:61]
	v_lshl_add_u64 v[124:125], s[8:9], 0, v[60:61]
	v_add_u32_e32 v60, s16, v100
	v_add_u32_e32 v61, v60, v107
	v_pk_mul_f32 v[26:27], v[112:113], v[26:27] op_sel_hi:[0,1]
	v_pk_mul_f32 v[24:25], v[112:113], v[24:25] op_sel_hi:[0,1]
	v_pk_mul_f32 v[30:31], v[112:113], v[30:31] op_sel_hi:[0,1]
	v_pk_mul_f32 v[28:29], v[112:113], v[28:29] op_sel_hi:[0,1]
	ds_read_b128 v[112:115], v99 offset:36864
	ds_read_b128 v[116:119], v99 offset:36928
	ds_read_b128 v[120:123], v61 offset:18432
	s_waitcnt lgkmcnt(0)
	v_mfma_f32_16x16x32_bf16 v[24:27], v[120:123], v[112:115], v[24:27]
	ds_read_b128 v[120:123], v61 offset:18496
	v_add_u32_e32 v60, v60, v108
	s_waitcnt lgkmcnt(0)
	v_mfma_f32_16x16x32_bf16 v[24:27], v[120:123], v[116:119], v[24:27]
	ds_read_b64 v[120:121], v109 offset:55296
	v_add3_u32 v111, s34, v82, v83
	v_add_u32_e32 v128, 0xfc00, v111
	s_waitcnt lgkmcnt(0)
	v_lshlrev_b32_e32 v122, 16, v120
	v_and_b32_e32 v123, 0xffff0000, v120
	v_lshlrev_b32_e32 v120, 16, v121
	v_and_b32_e32 v121, 0xffff0000, v121
	v_pk_fma_f32 v[24:25], v[46:47], v[122:123], v[24:25]
	v_pk_fma_f32 v[26:27], v[46:47], v[120:121], v[26:27]
	v_cvt_pk_bf16_f32 v24, v24, v25
	v_cvt_pk_bf16_f32 v25, v26, v27
	v_lshl_add_u64 v[120:121], v[124:125], 0, v[168:169]
	global_store_dwordx2 v[120:121], v[24:25], off offset:512
	ds_read_b128 v[24:27], v60 offset:18432
	s_waitcnt lgkmcnt(0)
	v_mfma_f32_16x16x32_bf16 v[24:27], v[24:27], v[112:115], v[28:31]
	s_nop 2
	ds_read_b128 v[28:31], v60 offset:18496
	v_add_u32_e32 v124, s17, v85
	v_add3_u32 v112, s34, v86, v83
	s_waitcnt lgkmcnt(0)
	v_mfma_f32_16x16x32_bf16 v[24:27], v[28:31], v[116:119], v[24:27]
	ds_read_b64 v[28:29], v110 offset:55296
	v_add3_u32 v113, s34, v89, v83
	s_mul_i32 s74, s74, 0x18920
	s_add_i32 s29, s29, 64
	s_cmpk_eq_i32 s31, 0x84
	s_waitcnt lgkmcnt(0)
	v_lshlrev_b32_e32 v30, 16, v28
	v_and_b32_e32 v31, 0xffff0000, v28
	v_lshlrev_b32_e32 v28, 16, v29
	v_and_b32_e32 v29, 0xffff0000, v29
	v_pk_fma_f32 v[24:25], v[46:47], v[30:31], v[24:25]
	v_pk_fma_f32 v[26:27], v[46:47], v[28:29], v[26:27]
	v_cvt_pk_bf16_f32 v24, v24, v25
	v_cvt_pk_bf16_f32 v25, v26, v27
	global_store_dwordx2 v[120:121], v[24:25], off offset:544
	v_add_u32_e32 v122, s17, v198
	v_add_u32_e32 v124, s17, v201
	v_add_u32_e32 v123, s74, v200
	v_mov_b32_e32 v154, 0xbfb8aa3b
	ds_read_b32 v131, v122 offset:128
	ds_read_b32 v133, v122 offset:528
	ds_read_b32 v135, v122 offset:928
	ds_read_b32 v137, v122 offset:1328
	ds_read_b32 v139, v122 offset:1728
	ds_read_b32 v141, v122 offset:2128
	ds_read_b128 v[156:159], v124
	ds_read_b32 v143, v122 offset:256
	ds_read_b32 v145, v122 offset:656
	ds_read_b32 v147, v122 offset:1056
	ds_read_b32 v149, v122 offset:1456
	ds_read_b32 v151, v122 offset:1856
	ds_read_b32 v153, v122 offset:2256
	s_waitcnt lgkmcnt(10)
	v_lshlrev_b32_e32 v130, 16, v131
	v_and_b32_e32 v131, 0xffff0000, v131
	v_lshlrev_b32_e32 v132, 16, v133
	v_and_b32_e32 v133, 0xffff0000, v133
	v_lshlrev_b32_e32 v134, 16, v135
	v_and_b32_e32 v135, 0xffff0000, v135
	s_waitcnt lgkmcnt(7)
	v_lshlrev_b32_e32 v136, 16, v137
	v_and_b32_e32 v137, 0xffff0000, v137
	v_lshlrev_b32_e32 v138, 16, v139
	v_and_b32_e32 v139, 0xffff0000, v139
	v_lshlrev_b32_e32 v140, 16, v141
	v_and_b32_e32 v141, 0xffff0000, v141
	v_pk_mul_f32 v[160:161], v[180:181], v[130:131]
	v_pk_mul_f32 v[162:163], v[180:181], v[132:133]
	v_pk_mul_f32 v[164:165], v[180:181], v[134:135]
	v_pk_mul_f32 v[166:167], v[180:181], v[136:137]
	v_pk_fma_f32 v[160:161], v[182:183], v[132:133], v[160:161]
	v_pk_fma_f32 v[162:163], v[182:183], v[134:135], v[162:163]
	v_pk_fma_f32 v[164:165], v[182:183], v[136:137], v[164:165]
	v_pk_fma_f32 v[166:167], v[182:183], v[138:139], v[166:167]
	v_pk_fma_f32 v[160:161], v[184:185], v[134:135], v[160:161]
	v_pk_fma_f32 v[162:163], v[184:185], v[136:137], v[162:163]
	v_pk_fma_f32 v[164:165], v[184:185], v[138:139], v[164:165]
	v_pk_fma_f32 v[166:167], v[184:185], v[140:141], v[166:167]
	v_pk_add_f32 v[160:161], v[186:187], v[160:161]
	v_pk_add_f32 v[162:163], v[186:187], v[162:163]
	v_pk_add_f32 v[164:165], v[186:187], v[164:165]
	v_pk_add_f32 v[166:167], v[186:187], v[166:167]
	v_pk_mul_f32 v[24:25], v[160:161], v[154:155] op_sel_hi:[1,0]
	v_pk_mul_f32 v[26:27], v[162:163], v[154:155] op_sel_hi:[1,0]
	v_pk_mul_f32 v[28:29], v[164:165], v[154:155] op_sel_hi:[1,0]
	v_pk_mul_f32 v[30:31], v[166:167], v[154:155] op_sel_hi:[1,0]
	v_exp_f32_e32 v24, v24
	v_exp_f32_e32 v26, v26
	v_exp_f32_e32 v28, v28
	v_exp_f32_e32 v30, v30
	v_exp_f32_e32 v25, v25
	v_exp_f32_e32 v27, v27
	v_exp_f32_e32 v29, v29
	v_exp_f32_e32 v31, v31
	v_pk_add_f32 v[24:25], v[24:25], 1.0 op_sel_hi:[1,0]
	v_pk_add_f32 v[26:27], v[26:27], 1.0 op_sel_hi:[1,0]
	v_pk_add_f32 v[28:29], v[28:29], 1.0 op_sel_hi:[1,0]
	v_pk_add_f32 v[30:31], v[30:31], 1.0 op_sel_hi:[1,0]
	v_rcp_f32_e32 v24, v24
	v_rcp_f32_e32 v26, v26
	v_rcp_f32_e32 v28, v28
	v_rcp_f32_e32 v30, v30
	v_rcp_f32_e32 v25, v25
	v_rcp_f32_e32 v27, v27
	v_rcp_f32_e32 v29, v29
	v_rcp_f32_e32 v31, v31
	v_pk_mul_f32 v[160:161], v[160:161], v[24:25]
	v_pk_mul_f32 v[162:163], v[162:163], v[26:27]
	v_pk_mul_f32 v[164:165], v[164:165], v[28:29]
	v_pk_mul_f32 v[166:167], v[166:167], v[30:31]
	v_cvt_pk_bf16_f32 v24, v160, v161
	v_cvt_pk_bf16_f32 v26, v162, v163
	v_cvt_pk_bf16_f32 v28, v164, v165
	v_cvt_pk_bf16_f32 v30, v166, v167
	ds_write_b32 v199, v24 offset:9216
	ds_write_b32 v199, v26 offset:9360
	ds_write_b32 v199, v28 offset:9504
	ds_write_b32 v199, v30 offset:9648
	s_waitcnt lgkmcnt(10)
	v_pk_mul_f32 v[112:113], v[160:161], v[156:157] op_sel_hi:[1,0]
	v_pk_mul_f32 v[114:115], v[162:163], v[156:157] op_sel:[0,1]
	v_pk_mul_f32 v[116:117], v[164:165], v[158:159] op_sel_hi:[1,0]
	v_pk_mul_f32 v[118:119], v[166:167], v[158:159] op_sel:[0,1]
	v_cvt_pk_bf16_f32 v24, v112, v114
	v_cvt_pk_bf16_f32 v25, v116, v118
	v_cvt_pk_bf16_f32 v26, v113, v115
	v_cvt_pk_bf16_f32 v27, v117, v119
	ds_write_b64 v123, v[24:25] offset:27648
	ds_write_b64 v123, v[26:27] offset:27792
	s_waitcnt lgkmcnt(9)
	v_lshlrev_b32_e32 v142, 16, v143
	v_and_b32_e32 v143, 0xffff0000, v143
	v_lshlrev_b32_e32 v144, 16, v145
	v_and_b32_e32 v145, 0xffff0000, v145
	v_lshlrev_b32_e32 v146, 16, v147
	v_and_b32_e32 v147, 0xffff0000, v147
	s_waitcnt lgkmcnt(6)
	v_lshlrev_b32_e32 v148, 16, v149
	v_and_b32_e32 v149, 0xffff0000, v149
	v_lshlrev_b32_e32 v150, 16, v151
	v_and_b32_e32 v151, 0xffff0000, v151
	v_lshlrev_b32_e32 v152, 16, v153
	v_and_b32_e32 v153, 0xffff0000, v153
	v_pk_mul_f32 v[160:161], v[188:189], v[142:143]
	v_pk_mul_f32 v[162:163], v[188:189], v[144:145]
	v_pk_mul_f32 v[164:165], v[188:189], v[146:147]
	v_pk_mul_f32 v[166:167], v[188:189], v[148:149]
	v_pk_fma_f32 v[160:161], v[190:191], v[144:145], v[160:161]
	v_pk_fma_f32 v[162:163], v[190:191], v[146:147], v[162:163]
	v_pk_fma_f32 v[164:165], v[190:191], v[148:149], v[164:165]
	v_pk_fma_f32 v[166:167], v[190:191], v[150:151], v[166:167]
	v_pk_fma_f32 v[160:161], v[192:193], v[146:147], v[160:161]
	v_pk_fma_f32 v[162:163], v[192:193], v[148:149], v[162:163]
	v_pk_fma_f32 v[164:165], v[192:193], v[150:151], v[164:165]
	v_pk_fma_f32 v[166:167], v[192:193], v[152:153], v[166:167]
	v_pk_add_f32 v[160:161], v[194:195], v[160:161]
	v_pk_add_f32 v[162:163], v[194:195], v[162:163]
	v_pk_add_f32 v[164:165], v[194:195], v[164:165]
	v_pk_add_f32 v[166:167], v[194:195], v[166:167]
	v_pk_mul_f32 v[24:25], v[160:161], v[154:155] op_sel_hi:[1,0]
	v_pk_mul_f32 v[26:27], v[162:163], v[154:155] op_sel_hi:[1,0]
	v_pk_mul_f32 v[28:29], v[164:165], v[154:155] op_sel_hi:[1,0]
	v_pk_mul_f32 v[30:31], v[166:167], v[154:155] op_sel_hi:[1,0]
	v_exp_f32_e32 v24, v24
	v_exp_f32_e32 v26, v26
	v_exp_f32_e32 v28, v28
	v_exp_f32_e32 v30, v30
	v_exp_f32_e32 v25, v25
	v_exp_f32_e32 v27, v27
	v_exp_f32_e32 v29, v29
	v_exp_f32_e32 v31, v31
	v_pk_add_f32 v[24:25], v[24:25], 1.0 op_sel_hi:[1,0]
	v_pk_add_f32 v[26:27], v[26:27], 1.0 op_sel_hi:[1,0]
	v_pk_add_f32 v[28:29], v[28:29], 1.0 op_sel_hi:[1,0]
	v_pk_add_f32 v[30:31], v[30:31], 1.0 op_sel_hi:[1,0]
	v_rcp_f32_e32 v24, v24
	v_rcp_f32_e32 v26, v26
	v_rcp_f32_e32 v28, v28
	v_rcp_f32_e32 v30, v30
	v_rcp_f32_e32 v25, v25
	v_rcp_f32_e32 v27, v27
	v_rcp_f32_e32 v29, v29
	v_rcp_f32_e32 v31, v31
	v_pk_mul_f32 v[160:161], v[160:161], v[24:25]
	v_pk_mul_f32 v[162:163], v[162:163], v[26:27]
	v_pk_mul_f32 v[164:165], v[164:165], v[28:29]
	v_pk_mul_f32 v[166:167], v[166:167], v[30:31]
	v_cvt_pk_bf16_f32 v24, v160, v161
	v_cvt_pk_bf16_f32 v26, v162, v163
	v_cvt_pk_bf16_f32 v28, v164, v165
	v_cvt_pk_bf16_f32 v30, v166, v167
	ds_write_b32 v199, v24 offset:0
	ds_write_b32 v199, v26 offset:144
	ds_write_b32 v199, v28 offset:288
	ds_write_b32 v199, v30 offset:432
	s_mov_b32 s35, s31
	v_add_u32_e32 v121, s16, v99
	v_mov_b32_e32 v24, s84
	s_waitcnt lgkmcnt(0)
	s_barrier
	ds_read_b32 v24, v24 offset:252
	s_waitcnt lgkmcnt(0)
	v_mul_f32_e32 v24, 0x3fb8aa3b, v24
	v_exp_f32_e32 v120, v24
	ds_read_b128 v[24:27], v121 offset:27648
	ds_read_b128 v[28:31], v61 offset:18432
	v_pk_mul_f32 v[18:19], v[18:19], v[120:121] op_sel_hi:[1,0]
	v_pk_mul_f32 v[16:17], v[16:17], v[120:121] op_sel_hi:[1,0]
	v_pk_mul_f32 v[22:23], v[22:23], v[120:121] op_sel_hi:[1,0]
	v_pk_mul_f32 v[20:21], v[20:21], v[120:121] op_sel_hi:[1,0]
	s_waitcnt lgkmcnt(0)
	v_mfma_f32_16x16x32_bf16 v[16:19], v[24:27], v[28:31], v[16:19]
	ds_read_b128 v[24:27], v121 offset:27712
	ds_read_b128 v[28:31], v61 offset:18496
	s_waitcnt lgkmcnt(0)
	v_mfma_f32_16x16x32_bf16 v[16:19], v[24:27], v[28:31], v[16:19]
	v_add_u32_e32 v26, v106, v107
	s_nop 6
	v_cvt_pk_bf16_f32 v24, v16, v17
	v_cvt_pk_bf16_f32 v25, v18, v19
	ds_write_b64 v26, v[24:25] offset:46080
	ds_read_b128 v[24:27], v121 offset:27648
	ds_read_b128 v[28:31], v60 offset:18432
	s_waitcnt lgkmcnt(0)
	v_mfma_f32_16x16x32_bf16 v[20:23], v[24:27], v[28:31], v[20:23]
	ds_read_b128 v[24:27], v121 offset:27712
	ds_read_b128 v[28:31], v60 offset:18496
	s_waitcnt lgkmcnt(0)
	v_mfma_f32_16x16x32_bf16 v[20:23], v[24:27], v[28:31], v[20:23]
	v_add_u32_e32 v26, v106, v108
	s_nop 6
	v_cvt_pk_bf16_f32 v24, v20, v21
	v_cvt_pk_bf16_f32 v25, v22, v23
	ds_write_b64 v26, v[24:25] offset:46080
	v_add_u32_e32 v122, s17, v198
	v_add_u32_e32 v124, s17, v201
	v_add_u32_e32 v124, 0xffffff00, v124
	v_add_u32_e32 v123, s74, v200
	v_mov_b32_e32 v154, 0xbfb8aa3b
	ds_read_b32 v131, v122 offset:0
	ds_read_b32 v133, v122 offset:400
	ds_read_b32 v135, v122 offset:800
	ds_read_b32 v137, v122 offset:1200
	ds_read_b32 v139, v122 offset:1600
	ds_read_b32 v141, v122 offset:2000
	ds_read_b128 v[156:159], v124
	s_waitcnt lgkmcnt(4)
	v_lshlrev_b32_e32 v130, 16, v131
	v_and_b32_e32 v131, 0xffff0000, v131
	v_lshlrev_b32_e32 v132, 16, v133
	v_and_b32_e32 v133, 0xffff0000, v133
	v_lshlrev_b32_e32 v134, 16, v135
	v_and_b32_e32 v135, 0xffff0000, v135
	s_waitcnt lgkmcnt(1)
	v_lshlrev_b32_e32 v136, 16, v137
	v_and_b32_e32 v137, 0xffff0000, v137
	v_lshlrev_b32_e32 v138, 16, v139
	v_and_b32_e32 v139, 0xffff0000, v139
	v_lshlrev_b32_e32 v140, 16, v141
	v_and_b32_e32 v141, 0xffff0000, v141
	v_pk_mul_f32 v[160:161], v[172:173], v[130:131]
	v_pk_mul_f32 v[162:163], v[172:173], v[132:133]
	v_pk_mul_f32 v[164:165], v[172:173], v[134:135]
	v_pk_mul_f32 v[166:167], v[172:173], v[136:137]
	v_pk_fma_f32 v[160:161], v[174:175], v[132:133], v[160:161]
	v_pk_fma_f32 v[162:163], v[174:175], v[134:135], v[162:163]
	v_pk_fma_f32 v[164:165], v[174:175], v[136:137], v[164:165]
	v_pk_fma_f32 v[166:167], v[174:175], v[138:139], v[166:167]
	v_pk_fma_f32 v[160:161], v[176:177], v[134:135], v[160:161]
	v_pk_fma_f32 v[162:163], v[176:177], v[136:137], v[162:163]
	v_pk_fma_f32 v[164:165], v[176:177], v[138:139], v[164:165]
	v_pk_fma_f32 v[166:167], v[176:177], v[140:141], v[166:167]
	v_pk_add_f32 v[160:161], v[178:179], v[160:161]
	v_pk_add_f32 v[162:163], v[178:179], v[162:163]
	v_pk_add_f32 v[164:165], v[178:179], v[164:165]
	v_pk_add_f32 v[166:167], v[178:179], v[166:167]
	v_pk_mul_f32 v[24:25], v[160:161], v[154:155] op_sel_hi:[1,0]
	v_pk_mul_f32 v[26:27], v[162:163], v[154:155] op_sel_hi:[1,0]
	v_pk_mul_f32 v[28:29], v[164:165], v[154:155] op_sel_hi:[1,0]
	v_pk_mul_f32 v[30:31], v[166:167], v[154:155] op_sel_hi:[1,0]
	v_exp_f32_e32 v24, v24
	v_exp_f32_e32 v26, v26
	v_exp_f32_e32 v28, v28
	v_exp_f32_e32 v30, v30
	v_exp_f32_e32 v25, v25
	v_exp_f32_e32 v27, v27
	v_exp_f32_e32 v29, v29
	v_exp_f32_e32 v31, v31
	v_pk_add_f32 v[24:25], v[24:25], 1.0 op_sel_hi:[1,0]
	v_pk_add_f32 v[26:27], v[26:27], 1.0 op_sel_hi:[1,0]
	v_pk_add_f32 v[28:29], v[28:29], 1.0 op_sel_hi:[1,0]
	v_pk_add_f32 v[30:31], v[30:31], 1.0 op_sel_hi:[1,0]
	v_rcp_f32_e32 v24, v24
	v_rcp_f32_e32 v26, v26
	v_rcp_f32_e32 v28, v28
	v_rcp_f32_e32 v30, v30
	v_rcp_f32_e32 v25, v25
	v_rcp_f32_e32 v27, v27
	v_rcp_f32_e32 v29, v29
	v_rcp_f32_e32 v31, v31
	v_pk_mul_f32 v[160:161], v[160:161], v[24:25]
	v_pk_mul_f32 v[162:163], v[162:163], v[26:27]
	v_pk_mul_f32 v[164:165], v[164:165], v[28:29]
	v_pk_mul_f32 v[166:167], v[166:167], v[30:31]
	v_cvt_pk_bf16_f32 v24, v160, v161
	v_cvt_pk_bf16_f32 v26, v162, v163
	v_cvt_pk_bf16_f32 v28, v164, v165
	v_cvt_pk_bf16_f32 v30, v166, v167
	ds_write_b32 v199, v24 offset:55296
	ds_write_b32 v199, v26 offset:55440
	ds_write_b32 v199, v28 offset:55584
	ds_write_b32 v199, v30 offset:55728
	s_waitcnt lgkmcnt(4)
	v_pk_mul_f32 v[112:113], v[160:161], v[156:157] op_sel_hi:[1,0]
	v_pk_mul_f32 v[114:115], v[162:163], v[156:157] op_sel:[0,1]
	v_pk_mul_f32 v[116:117], v[164:165], v[158:159] op_sel_hi:[1,0]
	v_pk_mul_f32 v[118:119], v[166:167], v[158:159] op_sel:[0,1]
	v_cvt_pk_bf16_f32 v24, v112, v114
	v_cvt_pk_bf16_f32 v25, v116, v118
	v_cvt_pk_bf16_f32 v26, v113, v115
	v_cvt_pk_bf16_f32 v27, v117, v119
	ds_write_b64 v123, v[24:25] offset:18432
	ds_write_b64 v123, v[26:27] offset:18576
	s_waitcnt lgkmcnt(0)
	s_barrier
	s_cbranch_scc1 .LBB0_474
.LBB0_443:
	s_and_b32 s34, s35, 1
	s_mul_i32 s16, s34, 0x6b00
	s_add_i32 s84, s16, 0
	s_add_i32 s84, s84, 0x16320
	ds_read_b128 v[132:135], v99
	v_add_u32_e32 v129, v100, v107
	ds_read_b128 v[136:139], v129 offset:9216
	ds_read_b128 v[140:143], v99 offset:64
	ds_read_b128 v[144:147], v129 offset:9280
	v_lshl_add_u32 v130, v48, 2, s84
	ds_read_b128 v[148:151], v130
	ds_read_b128 v[152:155], v129 offset:46080
	ds_read_b128 v[156:159], v129 offset:46144
	v_add_u32_e32 v131, v100, v108
	ds_read_b128 v[160:163], v131 offset:9280
	ds_read_b128 v[164:167], v131 offset:9216
	ds_read_b128 v[204:207], v130 offset:64
	v_lshl_add_u32 v24, v98, 2, s84
	ds_read_b32 v61, v24
	s_add_i32 s31, s35, 1
	s_cmpk_eq_i32 s35, 0x83
	s_waitcnt lgkmcnt(0)
	v_mfma_f32_16x16x32_bf16 v[24:27], v[136:139], v[132:135], 0
	v_mfma_f32_16x16x32_bf16 v[24:27], v[144:147], v[140:143], v[24:27]
	v_sub_f32_e32 v116, v61, v148
	v_mul_f32_e32 v116, 0x3fb8aa3b, v116
	v_exp_f32_e32 v116, v116
	s_nop 2
	s_nop 1
	v_mul_f32_e32 v24, v24, v116
	v_cndmask_b32_e64 v116, v24, 0, s[58:59]
	v_sub_f32_e32 v24, v61, v149
	v_mul_f32_e32 v24, 0x3fb8aa3b, v24
	v_exp_f32_e32 v24, v24
	s_nop 0
	v_mul_f32_e32 v24, v25, v24
	v_cndmask_b32_e64 v117, 0, v24, s[60:61]
	v_sub_f32_e32 v24, v61, v150
	v_sub_f32_e32 v25, v61, v151
	v_mul_f32_e32 v24, 0x3fb8aa3b, v24
	v_mul_f32_e32 v25, 0x3fb8aa3b, v25
	v_exp_f32_e32 v24, v24
	v_exp_f32_e32 v25, v25
	s_nop 0
	v_pk_mul_f32 v[24:25], v[26:27], v[24:25]
	s_nop 0
	v_cvt_pk_bf16_f32 v24, v24, v25
	v_cndmask_b32_e64 v25, v24, 0, s[64:65]
	v_lshrrev_b32_e32 v24, 16, v24
	v_cndmask_b32_e64 v24, v24, 0, s[62:63]
	v_cvt_pk_bf16_f32 v26, v116, v117
	v_perm_b32 v27, v24, v25, s24
	ds_write_b64 v109, v[26:27] offset:36864
	v_mfma_f32_16x16x32_bf16 v[24:27], v[152:155], v[132:135], 0
	v_add_u32_e32 v60, v100, v108
	v_mfma_f32_16x16x32_bf16 v[24:27], v[156:159], v[140:143], v[24:27]
	v_mfma_f32_16x16x32_bf16 v[116:119], v[164:167], v[132:135], 0
	v_mfma_f32_16x16x32_bf16 v[116:119], v[160:163], v[140:143], v[116:119]
	v_sub_f32_e32 v111, v61, v204
	v_mul_f32_e32 v111, 0x3fb8aa3b, v111
	v_exp_f32_e32 v111, v111
	s_nop 2
	s_nop 1
	v_mul_f32_e32 v111, v116, v111
	v_sub_f32_e32 v116, v61, v205
	v_mul_f32_e32 v116, 0x3fb8aa3b, v116
	v_exp_f32_e32 v116, v116
	v_cndmask_b32_e64 v111, v111, 0, s[66:67]
	v_mul_f32_e32 v116, v117, v116
	v_cndmask_b32_e64 v120, 0, v116, s[68:69]
	v_sub_f32_e32 v116, v61, v206
	v_sub_f32_e32 v117, v61, v207
	v_mul_f32_e32 v116, 0x3fb8aa3b, v116
	v_mul_f32_e32 v117, 0x3fb8aa3b, v117
	v_exp_f32_e32 v116, v116
	v_exp_f32_e32 v117, v117
	s_nop 0
	v_pk_mul_f32 v[116:117], v[118:119], v[116:117]
	v_cvt_pk_bf16_f32 v118, v111, v120
	v_cvt_pk_bf16_f32 v111, v116, v117
	v_cndmask_b32_e64 v116, v111, 0, s[72:73]
	v_lshrrev_b32_e32 v111, 16, v111
	v_cndmask_b32_e64 v111, v111, 0, s[70:71]
	v_perm_b32 v119, v111, v116, s24
	ds_write_b64 v110, v[118:119] offset:36864
	ds_read_b128 v[116:119], v60 offset:46080
	s_waitcnt lgkmcnt(0)
	v_mfma_f32_16x16x32_bf16 v[28:31], v[116:119], v[132:135], 0
	ds_read_b128 v[116:119], v60 offset:46144
	s_waitcnt lgkmcnt(0)
	v_mfma_f32_16x16x32_bf16 v[28:31], v[116:119], v[140:143], v[28:31]
	s_cbranch_scc1 .LBB0_470
	s_xor_b32 s16, s34, 1
	s_mulk_i32 s16, 0x6b00
	s_add_i32 s17, s16, 0
	v_add_u32_e32 v60, s17, v71
	v_add3_u32 v60, v60, v72, v73
	s_waitcnt vmcnt(0)
	s_waitcnt vmcnt(4)
	ds_write_b128 v60, v[0:3] offset:64912
	v_add_u32_e32 v60, s17, v74
	v_add3_u32 v60, v60, v75, v76
	s_waitcnt vmcnt(3)
	ds_write_b128 v60, v[4:7] offset:64912
	v_add_u32_e32 v60, s17, v77
	v_add3_u32 v60, v60, v78, v79
	s_waitcnt vmcnt(2)
	ds_write_b128 v60, v[8:11] offset:64912
	s_and_saveexec_b64 s[78:79], s[42:43]
	s_cbranch_execz .LBB0_447
	s_add_i32 s36, s35, -3
	s_cmp_gt_u32 s35, 2
	s_cselect_b32 s36, s36, s31
	s_cselect_b32 s37, 0x2000, s23
	v_lshl_add_u32 v60, s36, 6, v104
	v_cmp_lt_i32_e32 vcc, -1, v60
	v_cmp_gt_i32_e64 s[74:75], s37, v60
	s_and_b64 vcc, vcc, s[74:75]
	v_add_u32_e32 v60, s17, v105
	s_waitcnt vmcnt(1)
	v_cndmask_b32_e32 v115, 0, v15, vcc
	v_cndmask_b32_e32 v114, 0, v14, vcc
	v_cndmask_b32_e32 v113, 0, v13, vcc
	v_cndmask_b32_e32 v112, 0, v12, vcc
	v_add3_u32 v60, v60, v72, v73
	ds_write_b128 v60, v[112:115] offset:64512
	s_or_b64 exec, exec, s[78:79]
	s_and_saveexec_b64 s[74:75], s[44:45]
	s_cbranch_execnz .LBB0_448

.LBB0_482:
	s_or_b64 exec, exec, s[8:9]
	s_ashr_i32 s29, s27, 3
	s_cmp_eq_u32 s28, 0
	v_ashrrev_i32_e32 v55, 3, v28
	s_cselect_b64 vcc, -1, 0
	v_sub_u32_e32 v0, 0xff, v55
	s_lshl_b32 s28, s29, 8
	v_cndmask_b32_e32 v0, v0, v55, vcc
	s_add_i32 s28, s28, 0x8000
	v_add_u32_e32 v2, s28, v0
	v_mov_b64_e32 v[0:1], s[12:13]
	v_and_b32_e32 v4, 7, v28
	v_mad_i64_i32 v[0:1], s[8:9], v2, s20, v[0:1]
	s_lshl_b32 s84, s17, 1
	v_lshl_add_u64 v[0:1], v[0:1], 0, s[84:85]
	v_lshlrev_b32_e32 v168, 4, v4
	v_lshrrev_b32_e32 v29, 2, v28
	s_movk_i32 s8, 0xff
	v_lshl_add_u64 v[14:15], v[0:1], 0, v[168:169]
	v_bfe_u32 v56, v28, 2, 6
	v_bitop3_b32 v0, v29, s8, 63 bitop3:0x6c
	v_cndmask_b32_e32 v0, v0, v56, vcc
	v_or_b32_e32 v2, s28, v0
	v_mov_b64_e32 v[0:1], s[14:15]
	v_mad_i64_i32 v[0:1], s[8:9], v2, s21, v[0:1]
	s_lshl_b32 s8, s16, 2
	s_mov_b32 s9, s85
	v_and_b32_e32 v2, 12, v5
	s_waitcnt lgkmcnt(0)
	s_barrier
	global_load_dwordx4 v[6:9], v[14:15], off
	global_load_dwordx4 v[10:13], v[14:15], off offset:512
	v_lshl_add_u64 v[0:1], v[0:1], 0, s[8:9]
	v_lshlrev_b32_e32 v16, 2, v2
	v_mov_b32_e32 v17, v169
	v_lshl_add_u64 v[0:1], v[0:1], 0, v[16:17]
	global_load_dwordx4 v[0:3], v[0:1], off
	s_nop 0
	global_load_dwordx4 v[20:23], v[14:15], off offset:1024
	s_movk_i32 s16, 0x90
	v_mul_lo_u32 v14, v55, s16
	s_waitcnt vmcnt(0)
	v_add3_u32 v57, 0, v14, v168
	v_and_b32_e32 v5, 0x3ffffff0, v5
	v_cmp_gt_i32_e64 s[40:41], s23, v28
	v_lshlrev_b32_e32 v30, 2, v5
	s_waitcnt vmcnt(3)
	ds_write_b128 v57, v[6:9]
	s_waitcnt vmcnt(2)
	ds_write_b128 v57, v[10:13] offset:9216
	v_lshlrev_b32_e32 v6, 1, v55
	v_mul_u32_u24_e32 v7, 0x480, v4
	v_add3_u32 v58, 0, v7, v6
	s_waitcnt vmcnt(0)
	ds_write_b16 v58, v20 offset:18432
	ds_write_b16_d16_hi v58, v20 offset:18576
	ds_write_b16 v58, v21 offset:18720
	ds_write_b16_d16_hi v58, v21 offset:18864
	ds_write_b16 v58, v22 offset:19008
	ds_write_b16_d16_hi v58, v22 offset:19152
	ds_write_b16 v58, v23 offset:19296
	ds_write_b16_d16_hi v58, v23 offset:19440
	s_and_saveexec_b64 s[16:17], s[40:41]
	s_add_i32 s30, 0, 0x12000
	v_add3_u32 v5, s30, v30, v16
	ds_write_b128 v5, v[0:3]
	s_or_b64 exec, exec, s[16:17]
	v_or_b32_e32 v12, 64, v56
	v_xor_b32_e32 v13, 0xbf, v56
	v_add_u32_e32 v0, 64, v55
	v_sub_u32_e32 v1, 0xbf, v55
	v_cndmask_b32_e32 v12, v13, v12, vcc
	v_cndmask_b32_e32 v0, v1, v0, vcc
	v_or_b32_e32 v14, s28, v12
	v_mov_b64_e32 v[12:13], s[14:15]
	v_add_u32_e32 v3, s28, v0
	v_mov_b64_e32 v[0:1], s[12:13]
	v_mad_i64_i32 v[12:13], s[16:17], v14, s21, v[12:13]
	v_lshlrev_b32_e32 v2, 3, v4
	v_ashrrev_i32_e32 v31, 6, v28
	v_mad_i64_i32 v[0:1], s[16:17], v3, s20, v[0:1]
	v_lshl_add_u64 v[12:13], v[12:13], 0, s[8:9]
	v_lshl_add_u64 v[0:1], v[0:1], 0, s[84:85]
	v_lshlrev_b32_e32 v168, 1, v2
	v_lshl_add_u64 v[12:13], v[12:13], 0, v[16:17]
	v_lshl_add_u32 v17, v31, 9, 0
	v_lshl_add_u64 v[8:9], v[0:1], 0, v[168:169]
	v_add_u32_e32 v59, 0x12000, v17
	global_load_dwordx4 v[0:3], v[8:9], off
	global_load_dwordx4 v[4:7], v[8:9], off offset:512
	s_nop 0
	global_load_dwordx4 v[8:11], v[8:9], off offset:1024
	v_readlane_b32 s9, v253, 46
	global_load_dwordx4 v[12:15], v[12:13], off
	s_waitcnt lgkmcnt(0)
	s_barrier
	ds_read_b128 v[20:23], v59
	ds_read_b128 v[24:27], v59 offset:16
	ds_read_b128 v[48:51], v59 offset:32
	ds_read_b128 v[60:63], v59 offset:48
	v_cmp_lt_i32_e64 s[42:43], 0, v31
	s_waitcnt lgkmcnt(3)
	v_mov_b32_e32 v52, v20
	s_waitcnt lgkmcnt(2)
	v_mov_b32_e32 v53, v24
	v_mov_b32_e32 v24, v21
	v_pk_mul_f32 v[20:21], v[34:35], v[24:25]
	v_mov_b32_e32 v24, v22
	v_pk_fma_f32 v[20:21], v[32:33], v[52:53], v[20:21]
	v_mov_b32_e32 v25, v26
	v_pk_fma_f32 v[20:21], v[36:37], v[24:25], v[20:21]
	v_mov_b32_e32 v26, v23
	v_pk_fma_f32 v[20:21], v[38:39], v[26:27], v[20:21]
	v_cmp_lt_i32_e64 s[44:45], 1, v31
	v_add_f32_e32 v17, v54, v20
	v_add_f32_e32 v17, v17, v21
	s_waitcnt lgkmcnt(0)
	v_mov_b32_e32 v21, v60
	v_mov_b32_e32 v60, v49
	v_mov_b32_e32 v20, v48
	v_pk_mul_f32 v[22:23], v[42:43], v[60:61]
	v_cmp_lt_i32_e64 s[46:47], 2, v31
	v_pk_fma_f32 v[20:21], v[40:41], v[20:21], v[22:23]
	v_mov_b32_e32 v22, v50
	v_mov_b32_e32 v23, v62
	v_pk_fma_f32 v[20:21], v[44:45], v[22:23], v[20:21]
	v_mov_b32_e32 v62, v51
	v_pk_fma_f32 v[20:21], v[46:47], v[62:63], v[20:21]
	v_cmp_lt_i32_e64 s[48:49], 3, v31
	v_add_f32_e32 v17, v17, v20
	v_add_f32_e32 v17, v17, v21
	v_min_f32_e32 v18, 0, v17
	v_mul_f32_e64 v17, |v17|, s19
	v_exp_f32_e32 v17, v17
	ds_read_b128 v[20:23], v59 offset:64
	ds_read_b128 v[24:27], v59 offset:80
	v_cmp_lt_i32_e64 s[50:51], 4, v31
	v_cmp_lt_i32_e64 s[52:53], 5, v31
	v_add_f32_e32 v17, 1.0, v17
	v_log_f32_e32 v17, v17
	s_waitcnt lgkmcnt(0)
	v_mov_b32_e32 v49, v24
	v_mov_b32_e32 v24, v21
	v_mov_b32_e32 v48, v20
	v_pk_mul_f32 v[20:21], v[34:35], v[24:25]
	v_mov_b32_e32 v24, v22
	v_pk_fma_f32 v[20:21], v[32:33], v[48:49], v[20:21]
	v_mov_b32_e32 v25, v26
	v_pk_fma_f32 v[20:21], v[36:37], v[24:25], v[20:21]
	v_mov_b32_e32 v26, v23
	v_fmac_f32_e32 v18, 0xbf317218, v17
	v_pk_fma_f32 v[20:21], v[38:39], v[26:27], v[20:21]
	v_fma_f32 v17, v18, s26, 0
	v_add_f32_e32 v18, v54, v20
	v_add_f32_e32 v18, v18, v21
	ds_read_b128 v[20:23], v59 offset:96
	ds_read_b128 v[24:27], v59 offset:112
	v_cmp_lt_i32_e64 s[54:55], 6, v31
	v_cmp_lt_i32_e64 s[56:57], 7, v31
	v_cmp_gt_u32_e64 s[58:59], 64, v28
	s_waitcnt lgkmcnt(1)
	v_mov_b32_e32 v48, v20
	s_waitcnt lgkmcnt(0)
	v_mov_b32_e32 v49, v24
	v_mov_b32_e32 v24, v21
	v_pk_mul_f32 v[20:21], v[42:43], v[24:25]
	v_mov_b32_e32 v24, v22
	v_pk_fma_f32 v[20:21], v[40:41], v[48:49], v[20:21]
	v_mov_b32_e32 v25, v26
	v_pk_fma_f32 v[20:21], v[44:45], v[24:25], v[20:21]
	v_mov_b32_e32 v26, v23
	v_pk_fma_f32 v[20:21], v[46:47], v[26:27], v[20:21]
	ds_read_b128 v[22:25], v59 offset:128
	ds_read_b128 v[48:51], v59 offset:144
	v_add_f32_e32 v18, v18, v20
	v_add_f32_e32 v18, v18, v21
	v_min_f32_e32 v20, 0, v18
	v_mul_f32_e64 v18, |v18|, s19
	v_exp_f32_e32 v18, v18
	s_waitcnt lgkmcnt(0)
	v_mov_b32_e32 v27, v48
	v_mov_b32_e32 v48, v23
	v_mov_b32_e32 v26, v22
	v_add_f32_e32 v18, 1.0, v18
	v_log_f32_e32 v18, v18
	v_pk_mul_f32 v[22:23], v[34:35], v[48:49]
	v_fmac_f32_e32 v20, 0xbf317218, v18
	v_pk_fma_f32 v[22:23], v[32:33], v[26:27], v[22:23]
	v_mov_b32_e32 v26, v24
	v_mov_b32_e32 v27, v50
	v_pk_fma_f32 v[22:23], v[36:37], v[26:27], v[22:23]
	v_mov_b32_e32 v50, v25
	v_pk_fma_f32 v[22:23], v[38:39], v[50:51], v[22:23]
	v_fmamk_f32 v20, v20, 0x3d800000, v17
	v_add_f32_e32 v18, v54, v22
	v_add_f32_e32 v18, v18, v23
	ds_read_b128 v[22:25], v59 offset:160
	ds_read_b128 v[48:51], v59 offset:176
	s_waitcnt lgkmcnt(1)
	v_mov_b32_e32 v26, v22
	s_waitcnt lgkmcnt(0)
	v_mov_b32_e32 v27, v48
	v_mov_b32_e32 v48, v23
	v_pk_mul_f32 v[22:23], v[42:43], v[48:49]
	s_nop 0
	v_pk_fma_f32 v[22:23], v[40:41], v[26:27], v[22:23]
	v_mov_b32_e32 v26, v24
	v_mov_b32_e32 v27, v50
	v_pk_fma_f32 v[22:23], v[44:45], v[26:27], v[22:23]
	v_mov_b32_e32 v50, v25
	v_pk_fma_f32 v[22:23], v[46:47], v[50:51], v[22:23]
	ds_read_b128 v[24:27], v59 offset:192
	ds_read_b128 v[48:51], v59 offset:208
	v_add_f32_e32 v18, v18, v22
	v_add_f32_e32 v18, v18, v23
	v_min_f32_e32 v21, 0, v18
	v_mul_f32_e64 v18, |v18|, s19
	v_exp_f32_e32 v18, v18
	s_waitcnt lgkmcnt(0)
	v_mov_b32_e32 v53, v48
	v_mov_b32_e32 v48, v25
	v_mov_b32_e32 v52, v24
	v_add_f32_e32 v18, 1.0, v18
	v_log_f32_e32 v18, v18
	v_pk_mul_f32 v[24:25], v[34:35], v[48:49]
	v_mov_b32_e32 v48, v26
	v_pk_fma_f32 v[24:25], v[32:33], v[52:53], v[24:25]
	v_mov_b32_e32 v49, v50
	v_pk_fma_f32 v[24:25], v[36:37], v[48:49], v[24:25]
	v_mov_b32_e32 v50, v27
	v_pk_fma_f32 v[24:25], v[38:39], v[50:51], v[24:25]
	v_fmac_f32_e32 v21, 0xbf317218, v18
	v_add_f32_e32 v18, v54, v24
	v_add_f32_e32 v18, v18, v25
	ds_read_b128 v[24:27], v59 offset:224
	ds_read_b128 v[48:51], v59 offset:240
	v_fmamk_f32 v22, v21, 0x3d800000, v20
	s_waitcnt lgkmcnt(1)
	v_mov_b32_e32 v52, v24
	s_waitcnt lgkmcnt(0)
	v_mov_b32_e32 v53, v48
	v_mov_b32_e32 v48, v25
	v_pk_mul_f32 v[24:25], v[42:43], v[48:49]
	v_mov_b32_e32 v48, v26
	v_pk_fma_f32 v[24:25], v[40:41], v[52:53], v[24:25]
	v_mov_b32_e32 v49, v50
	v_pk_fma_f32 v[24:25], v[44:45], v[48:49], v[24:25]
	v_mov_b32_e32 v50, v27
	v_pk_fma_f32 v[24:25], v[46:47], v[50:51], v[24:25]
	s_nop 0
	v_add_f32_e32 v18, v18, v24
	v_add_f32_e32 v18, v18, v25
	v_min_f32_e32 v21, 0, v18
	v_mul_f32_e64 v18, |v18|, s19
	ds_read_b128 v[24:27], v59 offset:256
	ds_read_b128 v[48:51], v59 offset:272
	v_exp_f32_e32 v18, v18
	s_waitcnt lgkmcnt(1)
	v_mov_b32_e32 v52, v24
	v_add_f32_e32 v18, 1.0, v18
	s_waitcnt lgkmcnt(0)
	v_mov_b32_e32 v53, v48
	v_mov_b32_e32 v48, v25
	v_log_f32_e32 v18, v18
	v_pk_mul_f32 v[24:25], v[34:35], v[48:49]
	v_mov_b32_e32 v48, v26
	v_pk_fma_f32 v[24:25], v[32:33], v[52:53], v[24:25]
	v_mov_b32_e32 v49, v50
	v_pk_fma_f32 v[24:25], v[36:37], v[48:49], v[24:25]
	v_mov_b32_e32 v50, v27
	v_pk_fma_f32 v[24:25], v[38:39], v[50:51], v[24:25]
	v_fmac_f32_e32 v21, 0xbf317218, v18
	v_add_f32_e32 v18, v54, v24
	v_add_f32_e32 v18, v18, v25
	ds_read_b128 v[24:27], v59 offset:288
	ds_read_b128 v[48:51], v59 offset:304
	v_fmamk_f32 v23, v21, 0x3d800000, v22
	s_waitcnt lgkmcnt(1)
	v_mov_b32_e32 v52, v24
	s_waitcnt lgkmcnt(0)
	v_mov_b32_e32 v53, v48
	v_mov_b32_e32 v48, v25
	v_pk_mul_f32 v[24:25], v[42:43], v[48:49]
	v_mov_b32_e32 v48, v26
	v_pk_fma_f32 v[24:25], v[40:41], v[52:53], v[24:25]
	v_mov_b32_e32 v49, v50
	v_pk_fma_f32 v[24:25], v[44:45], v[48:49], v[24:25]
	v_mov_b32_e32 v50, v27
	v_pk_fma_f32 v[24:25], v[46:47], v[50:51], v[24:25]
	ds_read_b128 v[48:51], v59 offset:320
	ds_read_b128 v[60:63], v59 offset:336
	v_add_f32_e32 v18, v18, v24
	v_add_f32_e32 v18, v18, v25
	v_min_f32_e32 v21, 0, v18
	v_mul_f32_e64 v18, |v18|, s19
	v_exp_f32_e32 v18, v18
	s_waitcnt lgkmcnt(0)
	v_mov_b32_e32 v27, v60
	v_mov_b32_e32 v60, v49
	v_mov_b32_e32 v26, v48
	v_pk_mul_f32 v[48:49], v[34:35], v[60:61]
	v_add_f32_e32 v18, 1.0, v18
	v_pk_fma_f32 v[26:27], v[32:33], v[26:27], v[48:49]
	v_mov_b32_e32 v48, v50
	v_mov_b32_e32 v49, v62
	v_pk_fma_f32 v[26:27], v[36:37], v[48:49], v[26:27]
	v_mov_b32_e32 v62, v51
	v_log_f32_e32 v18, v18
	v_pk_fma_f32 v[26:27], v[38:39], v[62:63], v[26:27]
	ds_read_b128 v[48:51], v59 offset:352
	ds_read_b128 v[60:63], v59 offset:368
	v_fmac_f32_e32 v21, 0xbf317218, v18
	v_add_f32_e32 v18, v54, v26
	v_add_f32_e32 v18, v18, v27
	s_waitcnt lgkmcnt(0)
	v_mov_b32_e32 v27, v60
	v_mov_b32_e32 v60, v49
	v_mov_b32_e32 v26, v48
	v_pk_mul_f32 v[48:49], v[42:43], v[60:61]
	v_fmamk_f32 v24, v21, 0x3d800000, v23
	v_pk_fma_f32 v[26:27], v[40:41], v[26:27], v[48:49]
	v_mov_b32_e32 v48, v50
	v_mov_b32_e32 v49, v62
	v_pk_fma_f32 v[26:27], v[44:45], v[48:49], v[26:27]
	v_mov_b32_e32 v62, v51
	v_pk_fma_f32 v[26:27], v[46:47], v[62:63], v[26:27]
	ds_read_b128 v[48:51], v59 offset:384
	ds_read_b128 v[60:63], v59 offset:400
	v_add_f32_e32 v18, v18, v26
	v_add_f32_e32 v18, v18, v27
	v_min_f32_e32 v21, 0, v18
	v_mul_f32_e64 v18, |v18|, s19
	v_exp_f32_e32 v18, v18
	s_waitcnt lgkmcnt(0)
	v_mov_b32_e32 v27, v60
	v_mov_b32_e32 v60, v49
	v_mov_b32_e32 v26, v48
	v_pk_mul_f32 v[48:49], v[34:35], v[60:61]
	v_add_f32_e32 v18, 1.0, v18
	v_pk_fma_f32 v[26:27], v[32:33], v[26:27], v[48:49]
	v_mov_b32_e32 v48, v50
	v_mov_b32_e32 v49, v62
	v_pk_fma_f32 v[26:27], v[36:37], v[48:49], v[26:27]
	v_mov_b32_e32 v62, v51
	v_log_f32_e32 v18, v18
	v_pk_fma_f32 v[26:27], v[38:39], v[62:63], v[26:27]
	ds_read_b128 v[48:51], v59 offset:416
	ds_read_b128 v[60:63], v59 offset:432
	v_fmac_f32_e32 v21, 0xbf317218, v18
	v_add_f32_e32 v18, v54, v26
	v_add_f32_e32 v18, v18, v27
	s_waitcnt lgkmcnt(0)
	v_mov_b32_e32 v27, v60
	v_mov_b32_e32 v60, v49
	v_mov_b32_e32 v26, v48
	v_pk_mul_f32 v[48:49], v[42:43], v[60:61]
	v_fmamk_f32 v25, v21, 0x3d800000, v24
	v_pk_fma_f32 v[26:27], v[40:41], v[26:27], v[48:49]
	v_mov_b32_e32 v48, v50
	v_mov_b32_e32 v49, v62
	v_pk_fma_f32 v[26:27], v[44:45], v[48:49], v[26:27]
	v_mov_b32_e32 v62, v51
	v_pk_fma_f32 v[26:27], v[46:47], v[62:63], v[26:27]
	ds_read_b128 v[48:51], v59 offset:448
	ds_read_b128 v[60:63], v59 offset:464
	v_add_f32_e32 v18, v18, v26
	v_add_f32_e32 v18, v18, v27
	v_min_f32_e32 v21, 0, v18
	v_mul_f32_e64 v18, |v18|, s19
	v_exp_f32_e32 v18, v18
	s_waitcnt lgkmcnt(0)
	v_mov_b32_e32 v53, v60
	v_mov_b32_e32 v60, v49
	v_mov_b32_e32 v52, v48
	v_add_f32_e32 v18, 1.0, v18
	v_log_f32_e32 v18, v18
	v_pk_mul_f32 v[48:49], v[34:35], v[60:61]
	v_fmac_f32_e32 v21, 0xbf317218, v18
	v_pk_fma_f32 v[48:49], v[32:33], v[52:53], v[48:49]
	v_mov_b32_e32 v52, v50
	v_mov_b32_e32 v53, v62
	v_pk_fma_f32 v[48:49], v[36:37], v[52:53], v[48:49]
	v_mov_b32_e32 v62, v51
	v_pk_fma_f32 v[48:49], v[38:39], v[62:63], v[48:49]
	v_fmamk_f32 v26, v21, 0x3d800000, v25
	v_add_f32_e32 v18, v54, v48
	v_add_f32_e32 v18, v18, v49
	ds_read_b128 v[48:51], v59 offset:480
	ds_read_b128 v[60:63], v59 offset:496
	s_waitcnt lgkmcnt(1)
	v_mov_b32_e32 v52, v48
	s_waitcnt lgkmcnt(0)
	v_mov_b32_e32 v53, v60
	v_mov_b32_e32 v60, v49
	v_pk_mul_f32 v[48:49], v[42:43], v[60:61]
	v_lshl_add_u32 v60, v28, 2, s9
	v_pk_fma_f32 v[48:49], v[40:41], v[52:53], v[48:49]
	v_mov_b32_e32 v52, v50
	v_mov_b32_e32 v53, v62
	v_pk_fma_f32 v[48:49], v[44:45], v[52:53], v[48:49]
	v_mov_b32_e32 v62, v51
	v_pk_fma_f32 v[48:49], v[46:47], v[62:63], v[48:49]
	v_lshl_add_u32 v61, v19, 2, s9
	v_add_f32_e32 v18, v18, v48
	v_add_f32_e32 v18, v18, v49
	v_min_f32_e32 v21, 0, v18
	v_mul_f32_e64 v18, |v18|, s19
	v_exp_f32_e32 v18, v18
	s_movk_i32 s9, 0x480
	v_add_f32_e32 v18, 1.0, v18
	v_log_f32_e32 v18, v18
	s_nop 0
	v_fmac_f32_e32 v21, 0xbf317218, v18
	v_fmamk_f32 v27, v21, 0x3d800000, v26
	ds_write_b32 v60, v27
	s_waitcnt lgkmcnt(0)
	s_barrier
	ds_read2st64_b32 v[48:49], v61 offset1:1
	s_waitcnt lgkmcnt(0)
	v_add_f32_e32 v18, 0, v48
	v_cndmask_b32_e64 v21, 0, v18, s[42:43]
	v_add_f32_e32 v48, v49, v21
	v_cndmask_b32_e64 v21, v21, v48, s[44:45]
	v_add_f32_e32 v18, v18, v49
	ds_read2st64_b32 v[48:49], v61 offset0:2 offset1:3
	s_waitcnt lgkmcnt(0)
	v_add_f32_e32 v50, v48, v21
	v_cndmask_b32_e64 v21, v21, v50, s[46:47]
	v_add_f32_e32 v18, v18, v48
	v_add_f32_e32 v48, v49, v21
	v_cndmask_b32_e64 v21, v21, v48, s[48:49]
	v_add_f32_e32 v18, v18, v49
	ds_read2st64_b32 v[48:49], v61 offset0:4 offset1:5
	s_waitcnt lgkmcnt(0)
	v_add_f32_e32 v50, v48, v21
	v_cndmask_b32_e64 v21, v21, v50, s[50:51]
	v_add_f32_e32 v18, v18, v48
	v_add_f32_e32 v48, v49, v21
	v_cndmask_b32_e64 v21, v21, v48, s[52:53]
	v_add_f32_e32 v18, v18, v49
	ds_read2st64_b32 v[48:49], v61 offset0:6 offset1:7
	s_waitcnt lgkmcnt(0)
	v_add_f32_e32 v50, v48, v21
	v_cndmask_b32_e64 v21, v21, v50, s[54:55]
	v_add_f32_e32 v18, v18, v48
	v_add_f32_e32 v48, v49, v21
	v_cndmask_b32_e64 v50, v21, v48, s[56:57]
	v_add_f32_e32 v18, v18, v49
	v_lshlrev_b32_e32 v21, 1, v19
	v_mul_lo_u32 v49, v31, s9
	v_add3_u32 v62, 0, v21, v49
	ds_read_u16 v21, v62
	v_add_f32_e32 v17, v17, v50
	v_mul_f32_e32 v48, 0xbfb8aa3b, v17
	v_mul_f32_e32 v17, 0x3fb8aa3b, v17
	v_exp_f32_e32 v17, v17
	s_waitcnt lgkmcnt(0)
	v_lshlrev_b32_e32 v21, 16, v21
	v_mul_f32_e32 v21, 0x3e000000, v21
	v_exp_f32_e32 v48, v48
	v_mul_f32_e32 v17, v21, v17
	v_cvt_pk_bf16_f32 v17, v17, s0
	ds_write_b16 v62, v17 offset:27648
	v_add_f32_e32 v17, v20, v50
	v_mul_f32_e32 v20, 0xbfb8aa3b, v17
	v_exp_f32_e32 v49, v20
	ds_read_u16 v20, v62 offset:144
	v_mul_f32_e32 v17, 0x3fb8aa3b, v17
	v_exp_f32_e32 v17, v17
	v_mul_f32_e32 v18, 0x3fb8aa3b, v18
	v_exp_f32_e32 v18, v18
	s_waitcnt lgkmcnt(0)
	v_lshlrev_b32_e32 v20, 16, v20
	v_mul_f32_e32 v20, 0x3e000000, v20
	v_mul_f32_e32 v17, v20, v17
	v_cvt_pk_bf16_f32 v17, v17, s0
	ds_write_b16 v62, v17 offset:27792
	ds_read_u16 v17, v62 offset:9216
	ds_read_u16 v20, v62 offset:9360
	s_waitcnt lgkmcnt(0)
	v_lshlrev_b32_e32 v21, 16, v20
	v_lshlrev_b32_e32 v20, 16, v17
	v_mul_f32_e32 v17, v48, v20
	v_cvt_pk_bf16_f32 v17, v17, s0
	ds_write_b16 v62, v17 offset:36864
	v_mul_f32_e32 v17, v49, v21
	v_pk_mul_f32 v[48:49], v[18:19], v[48:49] op_sel_hi:[0,1]
	v_cvt_pk_bf16_f32 v17, v17, s0
	v_pk_mul_f32 v[20:21], v[48:49], v[20:21]
	ds_read_u16 v48, v62 offset:288
	ds_read_u16 v49, v62 offset:432
	ds_write_b16 v62, v17 offset:37008
	v_add_f32_e32 v17, v22, v50
	v_mul_f32_e32 v22, 0xbfb8aa3b, v17
	v_mul_f32_e32 v17, 0x3fb8aa3b, v17
	v_exp_f32_e32 v17, v17
	s_waitcnt lgkmcnt(2)
	v_lshlrev_b32_e32 v48, 16, v48
	v_mul_f32_e32 v48, 0x3e000000, v48
	s_waitcnt lgkmcnt(1)
	v_lshlrev_b32_e32 v49, 16, v49
	v_mul_f32_e32 v17, v17, v48
	v_cvt_pk_bf16_f32 v17, v17, s0
	ds_write_b16 v62, v17 offset:27936
	v_add_f32_e32 v17, v23, v50
	v_mul_f32_e32 v23, 0xbfb8aa3b, v17
	v_mul_f32_e32 v17, 0x3fb8aa3b, v17
	v_exp_f32_e32 v17, v17
	v_mul_f32_e32 v49, 0x3e000000, v49
	ds_read_u16 v48, v62 offset:9504
	v_exp_f32_e32 v22, v22
	v_mul_f32_e32 v17, v17, v49
	v_cvt_pk_bf16_f32 v17, v17, s0
	ds_write_b16 v62, v17 offset:28080
	ds_read_u16 v17, v62 offset:9648
	v_exp_f32_e32 v23, v23
	s_waitcnt lgkmcnt(2)
	v_lshlrev_b32_e32 v48, 16, v48
	v_cvt_pk_bf16_f32 v20, v20, v21
	s_waitcnt lgkmcnt(0)
	v_lshlrev_b32_e32 v49, 16, v17
	v_mul_f32_e32 v17, v22, v48
	v_cvt_pk_bf16_f32 v17, v17, s0
	ds_write_b16 v62, v17 offset:37152
	v_mul_f32_e32 v17, v23, v49
	v_pk_mul_f32 v[22:23], v[18:19], v[22:23] op_sel_hi:[0,1]
	v_cvt_pk_bf16_f32 v17, v17, s0
	v_pk_mul_f32 v[22:23], v[22:23], v[48:49]
	ds_read_u16 v48, v62 offset:576
	ds_write_b16 v62, v17 offset:37296
	v_add_f32_e32 v17, v24, v50
	v_mul_f32_e32 v24, 0xbfb8aa3b, v17
	v_mul_f32_e32 v17, 0x3fb8aa3b, v17
	v_exp_f32_e32 v17, v17
	s_waitcnt lgkmcnt(1)
	v_lshlrev_b32_e32 v48, 16, v48
	v_mul_f32_e32 v48, 0x3e000000, v48
	v_exp_f32_e32 v24, v24
	v_mul_f32_e32 v17, v17, v48
	v_cvt_pk_bf16_f32 v17, v17, s0
	ds_read_u16 v48, v62 offset:720
	ds_write_b16 v62, v17 offset:28224
	v_add_f32_e32 v17, v25, v50
	v_mul_f32_e32 v25, 0xbfb8aa3b, v17
	v_mul_f32_e32 v17, 0x3fb8aa3b, v17
	v_exp_f32_e32 v17, v17
	s_waitcnt lgkmcnt(1)
	v_lshlrev_b32_e32 v48, 16, v48
	v_mul_f32_e32 v48, 0x3e000000, v48
	v_exp_f32_e32 v25, v25
	v_mul_f32_e32 v17, v17, v48
	v_cvt_pk_bf16_f32 v17, v17, s0
	ds_write_b16 v62, v17 offset:28368
	ds_read_u16 v17, v62 offset:9792
	ds_read_u16 v48, v62 offset:9936
	v_cvt_pk_bf16_f32 v21, v22, v23
	s_waitcnt lgkmcnt(0)
	v_lshlrev_b32_e32 v49, 16, v48
	v_lshlrev_b32_e32 v48, 16, v17
	v_mul_f32_e32 v17, v24, v48
	v_cvt_pk_bf16_f32 v17, v17, s0
	ds_write_b16 v62, v17 offset:37440
	v_mul_f32_e32 v17, v25, v49
	v_pk_mul_f32 v[24:25], v[18:19], v[24:25] op_sel_hi:[0,1]
	v_cvt_pk_bf16_f32 v17, v17, s0
	v_pk_mul_f32 v[24:25], v[24:25], v[48:49]
	ds_read_u16 v48, v62 offset:864
	ds_write_b16 v62, v17 offset:37584
	v_add_f32_e32 v17, v26, v50
	v_mul_f32_e32 v26, 0xbfb8aa3b, v17
	v_mul_f32_e32 v17, 0x3fb8aa3b, v17
	v_exp_f32_e32 v17, v17
	s_waitcnt lgkmcnt(1)
	v_lshlrev_b32_e32 v48, 16, v48
	v_mul_f32_e32 v48, 0x3e000000, v48
	v_exp_f32_e32 v26, v26
	v_mul_f32_e32 v17, v17, v48
	v_cvt_pk_bf16_f32 v17, v17, s0
	ds_write_b16 v62, v17 offset:28512
	ds_read_u16 v48, v62 offset:10080
	ds_read_u16 v49, v62 offset:1008
	v_add_f32_e32 v17, v27, v50
	v_mul_f32_e32 v27, 0xbfb8aa3b, v17
	v_mul_f32_e32 v17, 0x3fb8aa3b, v17
	v_exp_f32_e32 v17, v17
	s_waitcnt lgkmcnt(0)
	v_lshlrev_b32_e32 v49, 16, v49
	v_mul_f32_e32 v49, 0x3e000000, v49
	v_exp_f32_e32 v27, v27
	v_mul_f32_e32 v17, v17, v49
	v_cvt_pk_bf16_f32 v17, v17, s0
	ds_write_b16 v62, v17 offset:28656
	ds_read_u16 v17, v62 offset:10224
	v_lshlrev_b32_e32 v48, 16, v48
	v_cvt_pk_bf16_f32 v22, v24, v25
	v_lshlrev_b32_e32 v24, 4, v31
	s_waitcnt lgkmcnt(0)
	v_lshlrev_b32_e32 v49, 16, v17
	v_mul_f32_e32 v17, v26, v48
	v_cvt_pk_bf16_f32 v17, v17, s0
	ds_write_b16 v62, v17 offset:37728
	v_mul_f32_e32 v17, v27, v49
	v_cvt_pk_bf16_f32 v17, v17, s0
	v_pk_mul_f32 v[26:27], v[18:19], v[26:27] op_sel_hi:[0,1]
	ds_write_b16 v62, v17 offset:37872
	v_pk_mul_f32 v[26:27], v[26:27], v[48:49]
	v_mul_u32_u24_e32 v17, 0x90, v19
	v_cvt_pk_bf16_f32 v23, v26, v27
	v_add3_u32 v63, 0, v17, v24
	ds_write_b128 v63, v[20:23] offset:46080
	s_and_saveexec_b64 s[16:17], s[58:59]
	v_lshl_add_u32 v17, v19, 2, 0
	v_add_u32_e32 v17, 0x13800, v17
	ds_write_b32 v17, v18
	s_or_b64 exec, exec, s[16:17]
	s_and_b64 s[16:17], vcc, exec
	s_mov_b32 s9, 0xab34000
	s_cselect_b32 s9, s9, 0xed34000
	v_readlane_b32 s30, v254, 53
	v_readlane_b32 s31, v254, 54
	s_add_u32 s17, s30, s9
	s_addc_u32 s34, s31, 0
	v_lshlrev_b32_e32 v17, 5, v31
	v_bfi_b32 v64, -16, v55, v28
	s_movk_i32 s9, 0x90
	s_add_u32 s30, s12, s84
	v_and_b32_e32 v18, 32, v17
	v_mul_lo_u32 v17, v64, s9
	s_addc_u32 s31, s13, 0
	v_add_u32_e32 v22, 0, v17
	v_and_b32_e32 v17, 48, v28
	s_add_u32 s8, s14, s8
	v_add_u32_e32 v65, v22, v17
	v_add_u32_e32 v66, 0, v17
	s_addc_u32 s9, s15, 0
	v_mov_b32_e32 v17, v169
	v_lshl_add_u64 v[50:51], s[8:9], 0, v[16:17]
	s_add_u32 s8, s17, s84
	v_and_b32_e32 v21, -16, v55
	v_and_b32_e32 v23, 12, v29
	v_lshl_add_u64 v[48:49], s[30:31], 0, v[168:169]
	s_addc_u32 s9, s34, 0
	s_add_i32 s30, 0, 0x13800
	v_lshl_add_u32 v67, v19, 2, s30
	v_lshlrev_b32_e32 v19, 2, v21
	v_lshlrev_b32_e32 v24, 2, v23
	v_and_b32_e32 v20, 15, v28
	v_add3_u32 v69, s30, v19, v24
	v_or_b32_e32 v19, v23, v21
	v_lshl_add_u32 v70, v19, 1, 0
	v_or_b32_e32 v19, v18, v20
	v_mul_u32_u24_e32 v71, 0x90, v19
	v_or_b32_e32 v19, v18, v23
	v_or_b32_e32 v21, 2, v19
	v_cmp_gt_i32_e64 s[64:65], v21, v64
	v_or_b32_e32 v21, 3, v19
	v_cmp_gt_i32_e64 s[66:67], v21, v64
	v_or_b32_e32 v21, 16, v18
	v_or_b32_e32 v20, v21, v20
	s_add_i32 s17, 0, 0x12000
	v_lshlrev_b32_e32 v168, 1, v23
	v_mul_u32_u24_e32 v72, 0x90, v20
	v_or_b32_e32 v20, v21, v23
	v_add3_u32 v68, s17, v30, v16
	v_lshl_add_u64 v[16:17], s[8:9], 0, v[168:169]
	v_or_b32_e32 v21, 2, v20
	v_lshlrev_b32_e32 v168, 1, v18
	v_cmp_gt_i32_e64 s[60:61], v19, v64
	v_cmp_lt_i32_e64 s[62:63], v19, v64
	v_lshlrev_b32_e32 v19, 1, v19
	v_cmp_gt_i32_e64 s[68:69], v20, v64
	v_cmp_lt_i32_e64 s[70:71], v20, v64
	v_cmp_gt_i32_e64 s[72:73], v21, v64
	v_or_b32_e32 v21, 3, v20
	v_lshlrev_b32_e32 v20, 1, v20
	v_lshl_add_u64 v[52:53], v[16:17], 0, v[168:169]
	v_mov_b32_e32 v16, 0
	s_mov_b32 s16, 0
	s_lshl_b32 s17, s29, 13
	v_cmp_gt_i32_e64 s[74:75], v21, v64
	v_add_u32_e32 v73, v22, v19
	v_add_u32_e32 v74, v22, v20
	s_mov_b32 s29, 0
	v_mov_b32_e32 v17, v16
	v_mov_b32_e32 v18, v16
	v_mov_b32_e32 v19, v16
	v_mov_b32_e32 v20, v16
	v_mov_b32_e32 v21, v16
	v_mov_b32_e32 v22, v16
	v_mov_b32_e32 v23, v16
	s_waitcnt lgkmcnt(0)
	s_barrier
	v_mov_b32_e32 v204, v32
	v_mov_b32_e32 v205, v34
	v_mov_b32_e32 v206, v36
	v_mov_b32_e32 v207, v38
	v_mov_b32_e32 v208, v33
	v_mov_b32_e32 v209, v35
	v_mov_b32_e32 v210, v37
	v_mov_b32_e32 v211, v39
	v_mov_b32_e32 v212, v40
	v_mov_b32_e32 v213, v42
	v_mov_b32_e32 v214, v44
	v_mov_b32_e32 v215, v46
	v_mov_b32_e32 v216, v41
	v_mov_b32_e32 v217, v43
	v_mov_b32_e32 v218, v45
	v_mov_b32_e32 v219, v47
	s_branch .LBB0_488

.LBB0_494:
	s_add_i32 s37, s16, 0xffffff00
	s_cmp_lt_u32 s29, 4
	s_mul_i32 s36, s35, 0x13a00
	s_mul_i32 s8, s35, 0x10200
	s_mul_i32 s9, s35, 0xa200
	s_cselect_b32 s35, s16, s37
	v_add_u32_e32 v75, s35, v64
	s_cselect_b32 s35, 0xff, s22
	v_sub_u32_e32 v76, s35, v75
	v_cndmask_b32_e32 v75, v76, v75, vcc
	s_cselect_b32 s35, s28, s17
	v_add_u32_e32 v76, s35, v75
	v_add_u32_e32 v90, s36, v66
	v_ashrrev_i32_e32 v77, 31, v76
	v_add_u32_e32 v75, v90, v71
	s_waitcnt lgkmcnt(0)
	s_barrier
	ds_read_b128 v[132:135], v65 offset:55296
	ds_read_b128 v[136:139], v65 offset:55360
	ds_read_b128 v[140:143], v75 offset:18432
	ds_read_b128 v[144:147], v75 offset:18496
	v_add_u32_e32 v129, v90, v72
	ds_read_b128 v[148:151], v129 offset:18432
	ds_read_b128 v[152:155], v129 offset:18496
	v_add_u32_e32 v131, s34, v59
	ds_read_b128 v[172:175], v131 offset:0
	ds_read_b128 v[176:179], v131 offset:16
	ds_read_b128 v[180:183], v131 offset:32
	ds_read_b128 v[184:187], v131 offset:48
	ds_read_b128 v[188:191], v131 offset:64
	ds_read_b128 v[192:195], v131 offset:80
	ds_read_b128 v[196:199], v131 offset:96
	ds_read_b128 v[200:203], v131 offset:112
	v_lshlrev_b64 v[88:89], 11, v[76:77]
	s_waitcnt lgkmcnt(10)
	v_mfma_f32_16x16x32_bf16 v[28:31], v[140:143], v[132:135], v[28:31]
	v_mfma_f32_16x16x32_bf16 v[28:31], v[144:147], v[136:139], v[28:31]
	s_nop 7
	v_cvt_pk_bf16_f32 v28, v28, v29
	v_cvt_pk_bf16_f32 v29, v30, v31
	v_lshl_add_u64 v[30:31], v[52:53], 0, v[88:89]
	global_store_dwordx2 v[30:31], v[28:29], off
	v_add_u32_e32 v28, v90, v72
	s_waitcnt lgkmcnt(8)
	v_mfma_f32_16x16x32_bf16 v[24:27], v[148:151], v[132:135], v[24:27]
	v_mfma_f32_16x16x32_bf16 v[24:27], v[152:155], v[136:139], v[24:27]
	s_nop 7
	v_cvt_pk_bf16_f32 v24, v24, v25
	v_cvt_pk_bf16_f32 v25, v26, v27
	global_store_dwordx2 v[30:31], v[24:25], off offset:32
	s_waitcnt lgkmcnt(5)
	v_pk_mul_f32 v[156:157], v[172:173], v[204:205]
	v_pk_mul_f32 v[158:159], v[174:175], v[206:207]
	v_pk_fma_f32 v[156:157], v[176:177], v[208:209], v[156:157]
	v_pk_fma_f32 v[158:159], v[178:179], v[210:211], v[158:159]
	v_pk_fma_f32 v[156:157], v[180:181], v[212:213], v[156:157]
	v_pk_fma_f32 v[158:159], v[182:183], v[214:215], v[158:159]
	s_waitcnt lgkmcnt(4)
	v_pk_fma_f32 v[156:157], v[184:185], v[216:217], v[156:157]
	v_pk_fma_f32 v[158:159], v[186:187], v[218:219], v[158:159]
	ds_read_b128 v[172:175], v131 offset:128
	ds_read_b128 v[176:179], v131 offset:144
	ds_read_b128 v[180:183], v131 offset:160
	ds_read_b128 v[184:187], v131 offset:176
	v_pk_add_f32 v[156:157], v[156:157], v[158:159]
	s_waitcnt lgkmcnt(6)
	v_pk_mul_f32 v[160:161], v[188:189], v[204:205]
	v_add_f32_e32 v164, v156, v157
	v_pk_mul_f32 v[162:163], v[190:191], v[206:207]
	v_add_f32_e32 v164, v54, v164
	v_pk_fma_f32 v[160:161], v[192:193], v[208:209], v[160:161]
	v_min_f32_e32 v166, 0, v164
	v_pk_fma_f32 v[162:163], v[194:195], v[210:211], v[162:163]
	v_mul_f32_e64 v164, |v164|, s19
	s_waitcnt lgkmcnt(4)
	v_pk_fma_f32 v[160:161], v[196:197], v[212:213], v[160:161]
	v_exp_f32_e32 v164, v164
	v_pk_fma_f32 v[162:163], v[198:199], v[214:215], v[162:163]
	v_pk_fma_f32 v[160:161], v[200:201], v[216:217], v[160:161]
	v_add_f32_e32 v164, 1.0, v164
	v_pk_fma_f32 v[162:163], v[202:203], v[218:219], v[162:163]
	v_log_f32_e32 v164, v164
	ds_read_b128 v[188:191], v131 offset:192
	ds_read_b128 v[192:195], v131 offset:208
	v_fmac_f32_e32 v166, 0xbf317218, v164
	ds_read_b128 v[196:199], v131 offset:224
	v_fma_f32 v25, v166, s26, 0
	ds_read_b128 v[200:203], v131 offset:240
	v_pk_add_f32 v[160:161], v[160:161], v[162:163]
	s_waitcnt lgkmcnt(6)
	v_pk_mul_f32 v[156:157], v[172:173], v[204:205]
	v_add_f32_e32 v165, v160, v161
	v_pk_mul_f32 v[158:159], v[174:175], v[206:207]
	v_add_f32_e32 v165, v54, v165
	v_pk_fma_f32 v[156:157], v[176:177], v[208:209], v[156:157]
	v_min_f32_e32 v167, 0, v165
	v_pk_fma_f32 v[158:159], v[178:179], v[210:211], v[158:159]
	v_mul_f32_e64 v165, |v165|, s19
	s_waitcnt lgkmcnt(4)
	v_pk_fma_f32 v[156:157], v[180:181], v[212:213], v[156:157]
	v_exp_f32_e32 v165, v165
	v_pk_fma_f32 v[158:159], v[182:183], v[214:215], v[158:159]
	v_pk_fma_f32 v[156:157], v[184:185], v[216:217], v[156:157]
	v_add_f32_e32 v165, 1.0, v165
	v_pk_fma_f32 v[158:159], v[186:187], v[218:219], v[158:159]
	v_log_f32_e32 v165, v165
	ds_read_b128 v[172:175], v131 offset:256
	ds_read_b128 v[176:179], v131 offset:272
	v_fmac_f32_e32 v167, 0xbf317218, v165
	ds_read_b128 v[180:183], v131 offset:288
	v_fmamk_f32 v26, v167, 0x3d800000, v25
	ds_read_b128 v[184:187], v131 offset:304
	v_pk_add_f32 v[156:157], v[156:157], v[158:159]
	s_waitcnt lgkmcnt(6)
	v_pk_mul_f32 v[160:161], v[188:189], v[204:205]
	v_add_f32_e32 v164, v156, v157
	v_pk_mul_f32 v[162:163], v[190:191], v[206:207]
	v_add_f32_e32 v164, v54, v164
	v_pk_fma_f32 v[160:161], v[192:193], v[208:209], v[160:161]
	v_min_f32_e32 v166, 0, v164
	v_pk_fma_f32 v[162:163], v[194:195], v[210:211], v[162:163]
	v_mul_f32_e64 v164, |v164|, s19
	s_waitcnt lgkmcnt(4)
	v_pk_fma_f32 v[160:161], v[196:197], v[212:213], v[160:161]
	v_exp_f32_e32 v164, v164
	v_pk_fma_f32 v[162:163], v[198:199], v[214:215], v[162:163]
	v_pk_fma_f32 v[160:161], v[200:201], v[216:217], v[160:161]
	v_add_f32_e32 v164, 1.0, v164
	v_pk_fma_f32 v[162:163], v[202:203], v[218:219], v[162:163]
	v_log_f32_e32 v164, v164
	ds_read_b128 v[188:191], v131 offset:320
	ds_read_b128 v[192:195], v131 offset:336
	v_fmac_f32_e32 v166, 0xbf317218, v164
	ds_read_b128 v[196:199], v131 offset:352
	v_fmamk_f32 v29, v166, 0x3d800000, v26
	ds_read_b128 v[200:203], v131 offset:368
	v_pk_add_f32 v[160:161], v[160:161], v[162:163]
	s_waitcnt lgkmcnt(6)
	v_pk_mul_f32 v[156:157], v[172:173], v[204:205]
	v_add_f32_e32 v165, v160, v161
	v_pk_mul_f32 v[158:159], v[174:175], v[206:207]
	v_add_f32_e32 v165, v54, v165
	v_pk_fma_f32 v[156:157], v[176:177], v[208:209], v[156:157]
	v_min_f32_e32 v167, 0, v165
	v_pk_fma_f32 v[158:159], v[178:179], v[210:211], v[158:159]
	v_mul_f32_e64 v165, |v165|, s19
	s_waitcnt lgkmcnt(4)
	v_pk_fma_f32 v[156:157], v[180:181], v[212:213], v[156:157]
	v_exp_f32_e32 v165, v165
	v_pk_fma_f32 v[158:159], v[182:183], v[214:215], v[158:159]
	v_pk_fma_f32 v[156:157], v[184:185], v[216:217], v[156:157]
	v_add_f32_e32 v165, 1.0, v165
	v_pk_fma_f32 v[158:159], v[186:187], v[218:219], v[158:159]
	v_log_f32_e32 v165, v165
	ds_read_b128 v[172:175], v131 offset:384
	ds_read_b128 v[176:179], v131 offset:400
	v_fmac_f32_e32 v167, 0xbf317218, v165
	ds_read_b128 v[180:183], v131 offset:416
	v_fmamk_f32 v30, v167, 0x3d800000, v29
	ds_read_b128 v[184:187], v131 offset:432
	v_pk_add_f32 v[156:157], v[156:157], v[158:159]
	s_waitcnt lgkmcnt(6)
	v_pk_mul_f32 v[160:161], v[188:189], v[204:205]
	v_add_f32_e32 v164, v156, v157
	v_pk_mul_f32 v[162:163], v[190:191], v[206:207]
	v_add_f32_e32 v164, v54, v164
	v_pk_fma_f32 v[160:161], v[192:193], v[208:209], v[160:161]
	v_min_f32_e32 v166, 0, v164
	v_pk_fma_f32 v[162:163], v[194:195], v[210:211], v[162:163]
	v_mul_f32_e64 v164, |v164|, s19
	s_waitcnt lgkmcnt(4)
	v_pk_fma_f32 v[160:161], v[196:197], v[212:213], v[160:161]
	v_exp_f32_e32 v164, v164
	v_pk_fma_f32 v[162:163], v[198:199], v[214:215], v[162:163]
	v_pk_fma_f32 v[160:161], v[200:201], v[216:217], v[160:161]
	v_add_f32_e32 v164, 1.0, v164
	v_pk_fma_f32 v[162:163], v[202:203], v[218:219], v[162:163]
	v_log_f32_e32 v164, v164
	ds_read_b128 v[188:191], v131 offset:448
	ds_read_b128 v[192:195], v131 offset:464
	v_fmac_f32_e32 v166, 0xbf317218, v164
	ds_read_b128 v[196:199], v131 offset:480
	v_fmamk_f32 v31, v166, 0x3d800000, v30
	ds_read_b128 v[200:203], v131 offset:496
	v_pk_add_f32 v[160:161], v[160:161], v[162:163]
	s_waitcnt lgkmcnt(6)
	v_pk_mul_f32 v[156:157], v[172:173], v[204:205]
	v_add_f32_e32 v165, v160, v161
	v_pk_mul_f32 v[158:159], v[174:175], v[206:207]
	v_add_f32_e32 v165, v54, v165
	v_pk_fma_f32 v[156:157], v[176:177], v[208:209], v[156:157]
	v_min_f32_e32 v167, 0, v165
	v_pk_fma_f32 v[158:159], v[178:179], v[210:211], v[158:159]
	v_mul_f32_e64 v165, |v165|, s19
	s_waitcnt lgkmcnt(4)
	v_pk_fma_f32 v[156:157], v[180:181], v[212:213], v[156:157]
	v_exp_f32_e32 v165, v165
	v_pk_fma_f32 v[158:159], v[182:183], v[214:215], v[158:159]
	v_pk_fma_f32 v[156:157], v[184:185], v[216:217], v[156:157]
	v_add_f32_e32 v165, 1.0, v165
	v_pk_fma_f32 v[158:159], v[186:187], v[218:219], v[158:159]
	v_log_f32_e32 v165, v165
	s_nop 0
	v_fmac_f32_e32 v167, 0xbf317218, v165
	v_fmamk_f32 v76, v167, 0x3d800000, v31
	v_pk_add_f32 v[156:157], v[156:157], v[158:159]
	s_waitcnt lgkmcnt(2)
	v_pk_mul_f32 v[160:161], v[188:189], v[204:205]
	v_add_f32_e32 v164, v156, v157
	v_pk_mul_f32 v[162:163], v[190:191], v[206:207]
	v_add_f32_e32 v164, v54, v164
	v_pk_fma_f32 v[160:161], v[192:193], v[208:209], v[160:161]
	v_min_f32_e32 v166, 0, v164
	v_pk_fma_f32 v[162:163], v[194:195], v[210:211], v[162:163]
	v_mul_f32_e64 v164, |v164|, s19
	s_waitcnt lgkmcnt(0)
	v_pk_fma_f32 v[160:161], v[196:197], v[212:213], v[160:161]
	v_exp_f32_e32 v164, v164
	v_pk_fma_f32 v[162:163], v[198:199], v[214:215], v[162:163]
	v_pk_fma_f32 v[160:161], v[200:201], v[216:217], v[160:161]
	v_add_f32_e32 v164, 1.0, v164
	v_pk_fma_f32 v[162:163], v[202:203], v[218:219], v[162:163]
	v_log_f32_e32 v164, v164
	s_nop 0
	v_fmac_f32_e32 v166, 0xbf317218, v164
	v_fmamk_f32 v77, v166, 0x3d800000, v76
	v_pk_add_f32 v[160:161], v[160:161], v[162:163]
	s_nop 0
	v_add_f32_e32 v165, v160, v161
	v_add_f32_e32 v165, v54, v165
	v_min_f32_e32 v167, 0, v165
	v_mul_f32_e64 v165, |v165|, s19
	v_exp_f32_e32 v165, v165
	s_nop 0
	v_add_f32_e32 v165, 1.0, v165
	v_log_f32_e32 v165, v165
	s_nop 0
	v_fmac_f32_e32 v167, 0xbf317218, v165
	v_fmamk_f32 v78, v167, 0x3d800000, v77
	v_add_u32_e32 v79, s31, v62
	v_add_u32_e32 v24, s9, v69
	ds_write_b32 v60, v78
	s_waitcnt lgkmcnt(0)
	s_barrier
	ds_read_b128 v[132:135], v24
	v_add_u32_e32 v129, s8, v65
	ds_read_b128 v[136:139], v129 offset:46080
	ds_read_b128 v[140:143], v75 offset:18432
	ds_read_b128 v[144:147], v129 offset:46144
	ds_read_b128 v[148:151], v75 offset:18496
	ds_read_b128 v[152:155], v129 offset:46080
	ds_read_b128 v[156:159], v28 offset:18432
	ds_read_b128 v[160:163], v129 offset:46144
	ds_read_b128 v[164:167], v28 offset:18496
	v_add_u32_e32 v27, v70, v71
	s_mul_i32 s8, s30, 0x10200
	s_waitcnt lgkmcnt(6)
	v_pk_mul_f32 v[16:17], v[16:17], v[132:133]
	v_pk_mul_f32 v[18:19], v[18:19], v[134:135]
	v_pk_mul_f32 v[20:21], v[20:21], v[132:133]
	v_pk_mul_f32 v[22:23], v[22:23], v[134:135]
	v_mfma_f32_16x16x32_bf16 v[16:19], v[136:139], v[140:143], v[16:19]
	s_waitcnt lgkmcnt(4)
	v_mfma_f32_16x16x32_bf16 v[16:19], v[144:147], v[148:151], v[16:19]
	s_nop 7
	v_cvt_pk_bf16_f32 v84, v16, v17
	v_cvt_pk_bf16_f32 v85, v18, v19
	ds_write_b64 v27, v[84:85] offset:64512
	s_waitcnt lgkmcnt(1)
	v_mfma_f32_16x16x32_bf16 v[20:23], v[152:155], v[156:159], v[20:23]
	v_add_u32_e32 v24, v70, v72
	v_mfma_f32_16x16x32_bf16 v[20:23], v[160:163], v[164:167], v[20:23]
	ds_read2st64_b32 v[130:131], v61 offset1:1
	ds_read2st64_b32 v[172:173], v61 offset0:2 offset1:3
	ds_read2st64_b32 v[174:175], v61 offset0:4 offset1:5
	ds_read2st64_b32 v[176:177], v61 offset0:6 offset1:7
	ds_read_u16 v178, v79
	ds_read_u16 v179, v79 offset:9216
	ds_read_u16 v180, v79 offset:144
	ds_read_u16 v181, v79 offset:9360
	ds_read_u16 v182, v79 offset:288
	ds_read_u16 v183, v79 offset:9504
	ds_read_u16 v184, v79 offset:432
	ds_read_u16 v185, v79 offset:9648
	ds_read_u16 v186, v79 offset:576
	ds_read_u16 v187, v79 offset:9792
	ds_read_u16 v188, v79 offset:720
	ds_read_u16 v189, v79 offset:9936
	ds_read_u16 v190, v79 offset:864
	ds_read_u16 v191, v79 offset:10080
	ds_read_u16 v192, v79 offset:1008
	ds_read_u16 v193, v79 offset:10224
	s_nop 7
	v_cvt_pk_bf16_f32 v80, v20, v21
	v_cvt_pk_bf16_f32 v81, v22, v23
	ds_write_b64 v24, v[80:81] offset:64512
	s_waitcnt lgkmcnt(12)
	v_add_f32_e32 v24, 0, v130
	v_cndmask_b32_e64 v27, 0, v24, s[42:43]
	v_add_f32_e32 v28, v131, v27
	v_add_f32_e32 v24, v24, v131
	v_cndmask_b32_e64 v27, v27, v28, s[44:45]
	v_add_f32_e32 v28, v172, v27
	v_cndmask_b32_e64 v27, v27, v28, s[46:47]
	v_add_f32_e32 v24, v24, v172
	v_add_f32_e32 v28, v173, v27
	v_add_f32_e32 v24, v24, v173
	v_cndmask_b32_e64 v27, v27, v28, s[48:49]
	v_add_f32_e32 v28, v174, v27
	v_cndmask_b32_e64 v27, v27, v28, s[50:51]
	v_add_f32_e32 v24, v24, v174
	v_add_f32_e32 v28, v175, v27
	v_add_f32_e32 v24, v24, v175
	v_cndmask_b32_e64 v27, v27, v28, s[52:53]
	v_add_f32_e32 v28, v176, v27
	v_cndmask_b32_e64 v27, v27, v28, s[54:55]
	v_add_f32_e32 v28, v177, v27
	v_cndmask_b32_e64 v75, v27, v28, s[56:57]
	v_add_f32_e32 v25, v25, v75
	v_mul_f32_e32 v27, 0xbfb8aa3b, v25
	v_add_f32_e32 v24, v24, v176
	v_exp_f32_e32 v80, v27
	v_mul_f32_e32 v25, 0x3fb8aa3b, v25
	v_exp_f32_e32 v25, v25
	v_add_f32_e32 v24, v24, v177
	v_lshlrev_b32_e32 v27, 16, v178
	v_mul_f32_e32 v27, 0x3e000000, v27
	v_mul_f32_e32 v25, v27, v25
	v_cvt_pk_bf16_f32 v25, v25, s0
	ds_write_b16 v62, v25 offset:27648
	v_add_f32_e32 v25, v26, v75
	v_lshlrev_b32_e32 v82, 16, v179
	v_mul_f32_e32 v26, 0xbfb8aa3b, v25
	v_exp_f32_e32 v81, v26
	v_mul_f32_e32 v26, v80, v82
	v_cvt_pk_bf16_f32 v26, v26, s0
	ds_write_b16 v62, v26 offset:36864
	v_mul_f32_e32 v25, 0x3fb8aa3b, v25
	v_exp_f32_e32 v25, v25
	v_mul_f32_e32 v24, 0x3fb8aa3b, v24
	v_lshlrev_b32_e32 v26, 16, v180
	v_mul_f32_e32 v26, 0x3e000000, v26
	v_mul_f32_e32 v25, v26, v25
	v_exp_f32_e32 v24, v24
	v_lshlrev_b32_e32 v83, 16, v181
	v_cvt_pk_bf16_f32 v25, v25, s0
	ds_write_b16 v62, v25 offset:27792
	v_mul_f32_e32 v25, v81, v83
	v_cvt_pk_bf16_f32 v25, v25, s0
	ds_write_b16 v62, v25 offset:37008
	v_pk_mul_f32 v[26:27], v[24:25], v[80:81] op_sel_hi:[0,1]
	v_add_f32_e32 v25, v29, v75
	v_mul_f32_e32 v28, 0xbfb8aa3b, v25
	v_mul_f32_e32 v25, 0x3fb8aa3b, v25
	v_exp_f32_e32 v25, v25
	v_exp_f32_e32 v28, v28
	v_lshlrev_b32_e32 v29, 16, v182
	v_mul_f32_e32 v29, 0x3e000000, v29
	v_mul_f32_e32 v25, v25, v29
	s_waitcnt lgkmcnt(12)
	v_lshlrev_b32_e32 v80, 16, v183
	v_cvt_pk_bf16_f32 v25, v25, s0
	ds_write_b16 v62, v25 offset:27936
	v_add_f32_e32 v25, v30, v75
	v_mul_f32_e32 v30, v28, v80
	v_cvt_pk_bf16_f32 v30, v30, s0
	ds_write_b16 v62, v30 offset:37152
	v_mul_f32_e32 v29, 0xbfb8aa3b, v25
	v_mul_f32_e32 v25, 0x3fb8aa3b, v25
	v_exp_f32_e32 v25, v25
	v_exp_f32_e32 v29, v29
	v_lshlrev_b32_e32 v30, 16, v184
	v_mul_f32_e32 v30, 0x3e000000, v30
	v_mul_f32_e32 v25, v25, v30
	v_lshlrev_b32_e32 v81, 16, v185
	v_cvt_pk_bf16_f32 v25, v25, s0
	ds_write_b16 v62, v25 offset:28080
	v_mul_f32_e32 v25, v29, v81
	v_cvt_pk_bf16_f32 v25, v25, s0
	ds_write_b16 v62, v25 offset:37296
	v_pk_mul_f32 v[28:29], v[24:25], v[28:29] op_sel_hi:[0,1]
	v_add_f32_e32 v25, v31, v75
	v_mul_f32_e32 v30, 0xbfb8aa3b, v25
	v_mul_f32_e32 v25, 0x3fb8aa3b, v25
	v_pk_mul_f32 v[28:29], v[28:29], v[80:81]
	v_exp_f32_e32 v25, v25
	v_exp_f32_e32 v30, v30
	v_lshlrev_b32_e32 v31, 16, v186
	v_mul_f32_e32 v31, 0x3e000000, v31
	v_mul_f32_e32 v25, v25, v31
	s_waitcnt lgkmcnt(12)
	v_lshlrev_b32_e32 v80, 16, v187
	v_cvt_pk_bf16_f32 v25, v25, s0
	ds_write_b16 v62, v25 offset:28224
	v_add_f32_e32 v25, v76, v75
	v_mul_f32_e32 v76, v30, v80
	v_cvt_pk_bf16_f32 v76, v76, s0
	ds_write_b16 v62, v76 offset:37440
	v_mul_f32_e32 v31, 0xbfb8aa3b, v25
	v_mul_f32_e32 v25, 0x3fb8aa3b, v25
	v_exp_f32_e32 v25, v25
	v_exp_f32_e32 v31, v31
	v_lshlrev_b32_e32 v76, 16, v188
	v_mul_f32_e32 v76, 0x3e000000, v76
	v_mul_f32_e32 v25, v25, v76
	v_lshlrev_b32_e32 v81, 16, v189
	v_cvt_pk_bf16_f32 v25, v25, s0
	ds_write_b16 v62, v25 offset:28368
	v_mul_f32_e32 v25, v31, v81
	v_cvt_pk_bf16_f32 v25, v25, s0
	ds_write_b16 v62, v25 offset:37584
	v_pk_mul_f32 v[30:31], v[24:25], v[30:31] op_sel_hi:[0,1]
	v_add_f32_e32 v25, v77, v75
	v_mul_f32_e32 v76, 0xbfb8aa3b, v25
	v_mul_f32_e32 v25, 0x3fb8aa3b, v25
	v_exp_f32_e32 v25, v25
	v_pk_mul_f32 v[30:31], v[30:31], v[80:81]
	v_lshlrev_b32_e32 v77, 16, v190
	v_mul_f32_e32 v77, 0x3e000000, v77
	v_exp_f32_e32 v76, v76
	v_mul_f32_e32 v25, v25, v77
	v_cvt_pk_bf16_f32 v25, v25, s0
	ds_write_b16 v62, v25 offset:28512
	v_add_f32_e32 v25, v78, v75
	s_waitcnt lgkmcnt(12)
	v_lshlrev_b32_e32 v80, 16, v191
	v_mul_f32_e32 v75, 0xbfb8aa3b, v25
	v_exp_f32_e32 v77, v75
	v_mul_f32_e32 v75, v76, v80
	v_cvt_pk_bf16_f32 v75, v75, s0
	ds_write_b16 v62, v75 offset:37728
	v_mul_f32_e32 v25, 0x3fb8aa3b, v25
	v_exp_f32_e32 v25, v25
	v_pk_mul_f32 v[26:27], v[26:27], v[82:83]
	v_lshlrev_b32_e32 v75, 16, v192
	v_mul_f32_e32 v75, 0x3e000000, v75
	v_mul_f32_e32 v25, v25, v75
	v_lshlrev_b32_e32 v81, 16, v193
	v_cvt_pk_bf16_f32 v25, v25, s0
	ds_write_b16 v62, v25 offset:28656
	v_mul_f32_e32 v25, v77, v81
	v_cvt_pk_bf16_f32 v25, v25, s0
	v_pk_mul_f32 v[76:77], v[24:25], v[76:77] op_sel_hi:[0,1]
	v_pk_mul_f32 v[76:77], v[76:77], v[80:81]
	ds_write_b16 v62, v25 offset:37872
	v_cvt_pk_bf16_f32 v26, v26, v27
	v_cvt_pk_bf16_f32 v27, v28, v29
	v_cvt_pk_bf16_f32 v28, v30, v31
	v_cvt_pk_bf16_f32 v29, v76, v77
	v_add_u32_e32 v25, s8, v63
	ds_write_b128 v25, v[26:29] offset:46080
	s_and_saveexec_b64 s[8:9], s[58:59]
	s_cbranch_execz .LBB0_487
	s_mul_i32 s30, s30, 0xa200
	v_add_u32_e32 v25, s30, v67
	ds_write_b32 v25, v24
	s_branch .LBB0_487
